# xattn QK stream: K ring 5 / Q ring 4 (deeper Q prefetch), with V hoist
# baseline (speedup 1.0000x reference)
.LBB0_760:
	v_add_u32_e32 v181, 0x11800, v211
	v_add_u32_e32 v220, 0x15e00, v211
	v_add_u32_e32 v221, 0x1a400, v211
	v_add_u32_e32 v222, 0x1ea00, v211
	global_load_dwordx4 v[212:215], v[170:171], off offset:-128
	global_load_dwordx4 v[216:219], v[170:171], off offset:-96
	global_load_dwordx4 v[248:251], v[170:171], off offset:-64
	global_load_dwordx4 v[244:247], v[170:171], off offset:-32
	ds_read_b128 v[224:227], v211
	ds_read_b128 v[228:231], v211 offset:17920
	ds_read_b128 v[232:235], v211 offset:35840
	ds_read_b128 v[236:239], v211 offset:53760
	ds_read_b128 v[240:243], v181
	s_waitcnt vmcnt(3) lgkmcnt(4)
	v_mfma_f32_32x32x16_bf16 v[112:127], v[224:227], v[212:215], 0
	ds_read_b128 v[224:227], v220
	s_waitcnt lgkmcnt(4)
	v_mfma_f32_32x32x16_bf16 v[96:111], v[228:231], v[212:215], 0
	ds_read_b128 v[228:231], v221
	s_waitcnt lgkmcnt(4)
	v_mfma_f32_32x32x16_bf16 v[80:95], v[232:235], v[212:215], 0
	ds_read_b128 v[232:235], v222
	s_waitcnt lgkmcnt(4)
	v_mfma_f32_32x32x16_bf16 v[64:79], v[236:239], v[212:215], 0
	ds_read_b128 v[236:239], v211 offset:32
	s_waitcnt lgkmcnt(4)
	v_mfma_f32_32x32x16_bf16 v[48:63], v[240:243], v[212:215], 0
	ds_read_b128 v[240:243], v211 offset:17952
	s_waitcnt lgkmcnt(4)
	v_mfma_f32_32x32x16_bf16 v[32:47], v[224:227], v[212:215], 0
	ds_read_b128 v[224:227], v211 offset:35872
	s_waitcnt lgkmcnt(4)
	v_mfma_f32_32x32x16_bf16 v[16:31], v[228:231], v[212:215], 0
	ds_read_b128 v[228:231], v211 offset:53792
	s_waitcnt lgkmcnt(4)
	v_mfma_f32_32x32x16_bf16 v[0:15], v[232:235], v[212:215], 0
	ds_read_b128 v[232:235], v181 offset:32
	global_load_dwordx4 v[212:215], v[170:171], off
	s_waitcnt vmcnt(3) lgkmcnt(4)
	v_mfma_f32_32x32x16_bf16 v[112:127], v[236:239], v[216:219], v[112:127]
	ds_read_b128 v[236:239], v220 offset:32
	s_waitcnt lgkmcnt(4)
	v_mfma_f32_32x32x16_bf16 v[96:111], v[240:243], v[216:219], v[96:111]
	ds_read_b128 v[240:243], v221 offset:32
	s_waitcnt lgkmcnt(4)
	v_mfma_f32_32x32x16_bf16 v[80:95], v[224:227], v[216:219], v[80:95]
	ds_read_b128 v[224:227], v222 offset:32
	s_waitcnt lgkmcnt(4)
	v_mfma_f32_32x32x16_bf16 v[64:79], v[228:231], v[216:219], v[64:79]
	ds_read_b128 v[228:231], v211 offset:64
	s_waitcnt lgkmcnt(4)
	v_mfma_f32_32x32x16_bf16 v[48:63], v[232:235], v[216:219], v[48:63]
	ds_read_b128 v[232:235], v211 offset:17984
	s_waitcnt lgkmcnt(4)
	v_mfma_f32_32x32x16_bf16 v[32:47], v[236:239], v[216:219], v[32:47]
	ds_read_b128 v[236:239], v211 offset:35904
	s_waitcnt lgkmcnt(4)
	v_mfma_f32_32x32x16_bf16 v[16:31], v[240:243], v[216:219], v[16:31]
	ds_read_b128 v[240:243], v211 offset:53824
	s_waitcnt lgkmcnt(4)
	v_mfma_f32_32x32x16_bf16 v[0:15], v[224:227], v[216:219], v[0:15]
	ds_read_b128 v[224:227], v181 offset:64
	global_load_dwordx4 v[216:219], v[170:171], off offset:32
	s_waitcnt vmcnt(3) lgkmcnt(4)
	v_mfma_f32_32x32x16_bf16 v[112:127], v[228:231], v[248:251], v[112:127]
	ds_read_b128 v[228:231], v220 offset:64
	s_waitcnt lgkmcnt(4)
	v_mfma_f32_32x32x16_bf16 v[96:111], v[232:235], v[248:251], v[96:111]
	ds_read_b128 v[232:235], v221 offset:64
	s_waitcnt lgkmcnt(4)
	v_mfma_f32_32x32x16_bf16 v[80:95], v[236:239], v[248:251], v[80:95]
	ds_read_b128 v[236:239], v222 offset:64
	s_waitcnt lgkmcnt(4)
	v_mfma_f32_32x32x16_bf16 v[64:79], v[240:243], v[248:251], v[64:79]
	ds_read_b128 v[240:243], v211 offset:96
	s_waitcnt lgkmcnt(4)
	v_mfma_f32_32x32x16_bf16 v[48:63], v[224:227], v[248:251], v[48:63]
	ds_read_b128 v[224:227], v211 offset:18016
	s_waitcnt lgkmcnt(4)
	v_mfma_f32_32x32x16_bf16 v[32:47], v[228:231], v[248:251], v[32:47]
	ds_read_b128 v[228:231], v211 offset:35936
	s_waitcnt lgkmcnt(4)
	v_mfma_f32_32x32x16_bf16 v[16:31], v[232:235], v[248:251], v[16:31]
	ds_read_b128 v[232:235], v211 offset:53856
	s_waitcnt lgkmcnt(4)
	v_mfma_f32_32x32x16_bf16 v[0:15], v[236:239], v[248:251], v[0:15]
	ds_read_b128 v[236:239], v181 offset:96
	global_load_dwordx4 v[248:251], v[170:171], off offset:64
	s_waitcnt vmcnt(3) lgkmcnt(4)
	v_mfma_f32_32x32x16_bf16 v[112:127], v[240:243], v[244:247], v[112:127]
	ds_read_b128 v[240:243], v220 offset:96
	s_waitcnt lgkmcnt(4)
	v_mfma_f32_32x32x16_bf16 v[96:111], v[224:227], v[244:247], v[96:111]
	ds_read_b128 v[224:227], v221 offset:96
	s_waitcnt lgkmcnt(4)
	v_mfma_f32_32x32x16_bf16 v[80:95], v[228:231], v[244:247], v[80:95]
	ds_read_b128 v[228:231], v222 offset:96
	s_waitcnt lgkmcnt(4)
	v_mfma_f32_32x32x16_bf16 v[64:79], v[232:235], v[244:247], v[64:79]
	ds_read_b128 v[232:235], v211 offset:128
	s_waitcnt lgkmcnt(4)
	v_mfma_f32_32x32x16_bf16 v[48:63], v[236:239], v[244:247], v[48:63]
	ds_read_b128 v[236:239], v211 offset:18048
	s_waitcnt lgkmcnt(4)
	v_mfma_f32_32x32x16_bf16 v[32:47], v[240:243], v[244:247], v[32:47]
	ds_read_b128 v[240:243], v211 offset:35968
	s_waitcnt lgkmcnt(4)
	v_mfma_f32_32x32x16_bf16 v[16:31], v[224:227], v[244:247], v[16:31]
	ds_read_b128 v[224:227], v211 offset:53888
	s_waitcnt lgkmcnt(4)
	v_mfma_f32_32x32x16_bf16 v[0:15], v[228:231], v[244:247], v[0:15]
	ds_read_b128 v[228:231], v181 offset:128
	global_load_dwordx4 v[244:247], v[170:171], off offset:96
	s_waitcnt vmcnt(3) lgkmcnt(4)
	v_mfma_f32_32x32x16_bf16 v[112:127], v[232:235], v[212:215], v[112:127]
	ds_read_b128 v[232:235], v220 offset:128
	s_waitcnt lgkmcnt(4)
	v_mfma_f32_32x32x16_bf16 v[96:111], v[236:239], v[212:215], v[96:111]
	ds_read_b128 v[236:239], v221 offset:128
	s_waitcnt lgkmcnt(4)
	v_mfma_f32_32x32x16_bf16 v[80:95], v[240:243], v[212:215], v[80:95]
	ds_read_b128 v[240:243], v222 offset:128
	s_waitcnt lgkmcnt(4)
	v_mfma_f32_32x32x16_bf16 v[64:79], v[224:227], v[212:215], v[64:79]
	ds_read_b128 v[224:227], v211 offset:160
	s_waitcnt lgkmcnt(4)
	v_mfma_f32_32x32x16_bf16 v[48:63], v[228:231], v[212:215], v[48:63]
	ds_read_b128 v[228:231], v211 offset:18080
	s_waitcnt lgkmcnt(4)
	v_mfma_f32_32x32x16_bf16 v[32:47], v[232:235], v[212:215], v[32:47]
	ds_read_b128 v[232:235], v211 offset:36000
	s_waitcnt lgkmcnt(4)
	v_mfma_f32_32x32x16_bf16 v[16:31], v[236:239], v[212:215], v[16:31]
	ds_read_b128 v[236:239], v211 offset:53920
	s_waitcnt lgkmcnt(4)
	v_mfma_f32_32x32x16_bf16 v[0:15], v[240:243], v[212:215], v[0:15]
	ds_read_b128 v[240:243], v181 offset:160
	global_load_dwordx4 v[212:215], v[170:171], off offset:128
	s_waitcnt vmcnt(3) lgkmcnt(4)
	v_mfma_f32_32x32x16_bf16 v[112:127], v[224:227], v[216:219], v[112:127]
	ds_read_b128 v[224:227], v220 offset:160
	s_waitcnt lgkmcnt(4)
	v_mfma_f32_32x32x16_bf16 v[96:111], v[228:231], v[216:219], v[96:111]
	ds_read_b128 v[228:231], v221 offset:160
	s_waitcnt lgkmcnt(4)
	v_mfma_f32_32x32x16_bf16 v[80:95], v[232:235], v[216:219], v[80:95]
	ds_read_b128 v[232:235], v222 offset:160
	s_waitcnt lgkmcnt(4)
	v_mfma_f32_32x32x16_bf16 v[64:79], v[236:239], v[216:219], v[64:79]
	ds_read_b128 v[236:239], v211 offset:192
	s_waitcnt lgkmcnt(4)
	v_mfma_f32_32x32x16_bf16 v[48:63], v[240:243], v[216:219], v[48:63]
	ds_read_b128 v[240:243], v211 offset:18112
	s_waitcnt lgkmcnt(4)
	v_mfma_f32_32x32x16_bf16 v[32:47], v[224:227], v[216:219], v[32:47]
	ds_read_b128 v[224:227], v211 offset:36032
	s_waitcnt lgkmcnt(4)
	v_mfma_f32_32x32x16_bf16 v[16:31], v[228:231], v[216:219], v[16:31]
	ds_read_b128 v[228:231], v211 offset:53952
	s_waitcnt lgkmcnt(4)
	v_mfma_f32_32x32x16_bf16 v[0:15], v[232:235], v[216:219], v[0:15]
	ds_read_b128 v[232:235], v181 offset:192
	global_load_dwordx4 v[216:219], v[170:171], off offset:160
	s_waitcnt vmcnt(3) lgkmcnt(4)
	v_mfma_f32_32x32x16_bf16 v[112:127], v[236:239], v[248:251], v[112:127]
	ds_read_b128 v[236:239], v220 offset:192
	s_waitcnt lgkmcnt(4)
	v_mfma_f32_32x32x16_bf16 v[96:111], v[240:243], v[248:251], v[96:111]
	ds_read_b128 v[240:243], v221 offset:192
	s_waitcnt lgkmcnt(4)
	v_mfma_f32_32x32x16_bf16 v[80:95], v[224:227], v[248:251], v[80:95]
	ds_read_b128 v[224:227], v222 offset:192
	s_waitcnt lgkmcnt(4)
	v_mfma_f32_32x32x16_bf16 v[64:79], v[228:231], v[248:251], v[64:79]
	ds_read_b128 v[228:231], v211 offset:224
	s_waitcnt lgkmcnt(4)
	v_mfma_f32_32x32x16_bf16 v[48:63], v[232:235], v[248:251], v[48:63]
	ds_read_b128 v[232:235], v211 offset:18144
	s_waitcnt lgkmcnt(4)
	v_mfma_f32_32x32x16_bf16 v[32:47], v[236:239], v[248:251], v[32:47]
	ds_read_b128 v[236:239], v211 offset:36064
	s_waitcnt lgkmcnt(4)
	v_mfma_f32_32x32x16_bf16 v[16:31], v[240:243], v[248:251], v[16:31]
	ds_read_b128 v[240:243], v211 offset:53984
	s_waitcnt lgkmcnt(4)
	v_mfma_f32_32x32x16_bf16 v[0:15], v[224:227], v[248:251], v[0:15]
	ds_read_b128 v[224:227], v181 offset:224
	global_load_dwordx4 v[248:251], v[170:171], off offset:192
	s_waitcnt vmcnt(3) lgkmcnt(4)
	v_mfma_f32_32x32x16_bf16 v[112:127], v[228:231], v[244:247], v[112:127]
	ds_read_b128 v[228:231], v220 offset:224
	s_waitcnt lgkmcnt(4)
	v_mfma_f32_32x32x16_bf16 v[96:111], v[232:235], v[244:247], v[96:111]
	ds_read_b128 v[232:235], v221 offset:224
	s_waitcnt lgkmcnt(4)
	v_mfma_f32_32x32x16_bf16 v[80:95], v[236:239], v[244:247], v[80:95]
	ds_read_b128 v[236:239], v222 offset:224
	s_waitcnt lgkmcnt(4)
	v_mfma_f32_32x32x16_bf16 v[64:79], v[240:243], v[244:247], v[64:79]
	ds_read_b128 v[240:243], v211 offset:256
	s_waitcnt lgkmcnt(4)
	v_mfma_f32_32x32x16_bf16 v[48:63], v[224:227], v[244:247], v[48:63]
	ds_read_b128 v[224:227], v211 offset:18176
	s_waitcnt lgkmcnt(4)
	v_mfma_f32_32x32x16_bf16 v[32:47], v[228:231], v[244:247], v[32:47]
	ds_read_b128 v[228:231], v211 offset:36096
	s_waitcnt lgkmcnt(4)
	v_mfma_f32_32x32x16_bf16 v[16:31], v[232:235], v[244:247], v[16:31]
	ds_read_b128 v[232:235], v211 offset:54016
	s_waitcnt lgkmcnt(4)
	v_mfma_f32_32x32x16_bf16 v[0:15], v[236:239], v[244:247], v[0:15]
	ds_read_b128 v[236:239], v181 offset:256
	global_load_dwordx4 v[244:247], v[170:171], off offset:224
	s_waitcnt vmcnt(3) lgkmcnt(4)
	v_mfma_f32_32x32x16_bf16 v[112:127], v[240:243], v[212:215], v[112:127]
	ds_read_b128 v[240:243], v220 offset:256
	s_waitcnt lgkmcnt(4)
	v_mfma_f32_32x32x16_bf16 v[96:111], v[224:227], v[212:215], v[96:111]
	ds_read_b128 v[224:227], v221 offset:256
	s_waitcnt lgkmcnt(4)
	v_mfma_f32_32x32x16_bf16 v[80:95], v[228:231], v[212:215], v[80:95]
	ds_read_b128 v[228:231], v222 offset:256
	s_waitcnt lgkmcnt(4)
	v_mfma_f32_32x32x16_bf16 v[64:79], v[232:235], v[212:215], v[64:79]
	ds_read_b128 v[232:235], v211 offset:288
	s_waitcnt lgkmcnt(4)
	v_mfma_f32_32x32x16_bf16 v[48:63], v[236:239], v[212:215], v[48:63]
	ds_read_b128 v[236:239], v211 offset:18208
	s_waitcnt lgkmcnt(4)
	v_mfma_f32_32x32x16_bf16 v[32:47], v[240:243], v[212:215], v[32:47]
	ds_read_b128 v[240:243], v211 offset:36128
	s_waitcnt lgkmcnt(4)
	v_mfma_f32_32x32x16_bf16 v[16:31], v[224:227], v[212:215], v[16:31]
	ds_read_b128 v[224:227], v211 offset:54048
	s_waitcnt lgkmcnt(4)
	v_mfma_f32_32x32x16_bf16 v[0:15], v[228:231], v[212:215], v[0:15]
	ds_read_b128 v[228:231], v181 offset:288
	global_load_dwordx4 v[212:215], v[170:171], off offset:256
	s_waitcnt vmcnt(3) lgkmcnt(4)
	v_mfma_f32_32x32x16_bf16 v[112:127], v[232:235], v[216:219], v[112:127]
	ds_read_b128 v[232:235], v220 offset:288
	s_waitcnt lgkmcnt(4)
	v_mfma_f32_32x32x16_bf16 v[96:111], v[236:239], v[216:219], v[96:111]
	ds_read_b128 v[236:239], v221 offset:288
	s_waitcnt lgkmcnt(4)
	v_mfma_f32_32x32x16_bf16 v[80:95], v[240:243], v[216:219], v[80:95]
	ds_read_b128 v[240:243], v222 offset:288
	s_waitcnt lgkmcnt(4)
	v_mfma_f32_32x32x16_bf16 v[64:79], v[224:227], v[216:219], v[64:79]
	ds_read_b128 v[224:227], v211 offset:320
	s_waitcnt lgkmcnt(4)
	v_mfma_f32_32x32x16_bf16 v[48:63], v[228:231], v[216:219], v[48:63]
	ds_read_b128 v[228:231], v211 offset:18240
	s_waitcnt lgkmcnt(4)
	v_mfma_f32_32x32x16_bf16 v[32:47], v[232:235], v[216:219], v[32:47]
	ds_read_b128 v[232:235], v211 offset:36160
	s_waitcnt lgkmcnt(4)
	v_mfma_f32_32x32x16_bf16 v[16:31], v[236:239], v[216:219], v[16:31]
	ds_read_b128 v[236:239], v211 offset:54080
	s_waitcnt lgkmcnt(4)
	v_mfma_f32_32x32x16_bf16 v[0:15], v[240:243], v[216:219], v[0:15]
	ds_read_b128 v[240:243], v181 offset:320
	global_load_dwordx4 v[216:219], v[170:171], off offset:288
	s_waitcnt vmcnt(3) lgkmcnt(4)
	v_mfma_f32_32x32x16_bf16 v[112:127], v[224:227], v[248:251], v[112:127]
	ds_read_b128 v[224:227], v220 offset:320
	s_waitcnt lgkmcnt(4)
	v_mfma_f32_32x32x16_bf16 v[96:111], v[228:231], v[248:251], v[96:111]
	ds_read_b128 v[228:231], v221 offset:320
	s_waitcnt lgkmcnt(4)
	v_mfma_f32_32x32x16_bf16 v[80:95], v[232:235], v[248:251], v[80:95]
	ds_read_b128 v[232:235], v222 offset:320
	s_waitcnt lgkmcnt(4)
	v_mfma_f32_32x32x16_bf16 v[64:79], v[236:239], v[248:251], v[64:79]
	ds_read_b128 v[236:239], v211 offset:352
	s_waitcnt lgkmcnt(4)
	v_mfma_f32_32x32x16_bf16 v[48:63], v[240:243], v[248:251], v[48:63]
	ds_read_b128 v[240:243], v211 offset:18272
	s_waitcnt lgkmcnt(4)
	v_mfma_f32_32x32x16_bf16 v[32:47], v[224:227], v[248:251], v[32:47]
	ds_read_b128 v[224:227], v211 offset:36192
	s_waitcnt lgkmcnt(4)
	v_mfma_f32_32x32x16_bf16 v[16:31], v[228:231], v[248:251], v[16:31]
	ds_read_b128 v[228:231], v211 offset:54112
	s_waitcnt lgkmcnt(4)
	v_mfma_f32_32x32x16_bf16 v[0:15], v[232:235], v[248:251], v[0:15]
	ds_read_b128 v[232:235], v181 offset:352
	global_load_dwordx4 v[248:251], v[170:171], off offset:320
	s_waitcnt vmcnt(3) lgkmcnt(4)
	v_mfma_f32_32x32x16_bf16 v[112:127], v[236:239], v[244:247], v[112:127]
	ds_read_b128 v[236:239], v220 offset:352
	s_waitcnt lgkmcnt(4)
	v_mfma_f32_32x32x16_bf16 v[96:111], v[240:243], v[244:247], v[96:111]
	ds_read_b128 v[240:243], v221 offset:352
	s_waitcnt lgkmcnt(4)
	v_mfma_f32_32x32x16_bf16 v[80:95], v[224:227], v[244:247], v[80:95]
	ds_read_b128 v[224:227], v222 offset:352
	s_waitcnt lgkmcnt(4)
	v_mfma_f32_32x32x16_bf16 v[64:79], v[228:231], v[244:247], v[64:79]
	ds_read_b128 v[228:231], v211 offset:384
	s_waitcnt lgkmcnt(4)
	v_mfma_f32_32x32x16_bf16 v[48:63], v[232:235], v[244:247], v[48:63]
	ds_read_b128 v[232:235], v211 offset:18304
	s_waitcnt lgkmcnt(4)
	v_mfma_f32_32x32x16_bf16 v[32:47], v[236:239], v[244:247], v[32:47]
	ds_read_b128 v[236:239], v211 offset:36224
	s_waitcnt lgkmcnt(4)
	v_mfma_f32_32x32x16_bf16 v[16:31], v[240:243], v[244:247], v[16:31]
	ds_read_b128 v[240:243], v211 offset:54144
	s_waitcnt lgkmcnt(4)
	v_mfma_f32_32x32x16_bf16 v[0:15], v[224:227], v[244:247], v[0:15]
	ds_read_b128 v[224:227], v181 offset:384
	global_load_dwordx4 v[244:247], v[170:171], off offset:352
	s_waitcnt vmcnt(3) lgkmcnt(4)
	v_mfma_f32_32x32x16_bf16 v[112:127], v[228:231], v[212:215], v[112:127]
	ds_read_b128 v[228:231], v220 offset:384
	s_waitcnt lgkmcnt(4)
	v_mfma_f32_32x32x16_bf16 v[96:111], v[232:235], v[212:215], v[96:111]
	ds_read_b128 v[232:235], v221 offset:384
	s_waitcnt lgkmcnt(4)
	v_mfma_f32_32x32x16_bf16 v[80:95], v[236:239], v[212:215], v[80:95]
	ds_read_b128 v[236:239], v222 offset:384
	s_waitcnt lgkmcnt(4)
	v_mfma_f32_32x32x16_bf16 v[64:79], v[240:243], v[212:215], v[64:79]
	ds_read_b128 v[240:243], v211 offset:416
	s_waitcnt lgkmcnt(4)
	v_mfma_f32_32x32x16_bf16 v[48:63], v[224:227], v[212:215], v[48:63]
	ds_read_b128 v[224:227], v211 offset:18336
	s_waitcnt lgkmcnt(4)
	v_mfma_f32_32x32x16_bf16 v[32:47], v[228:231], v[212:215], v[32:47]
	ds_read_b128 v[228:231], v211 offset:36256
	s_waitcnt lgkmcnt(4)
	v_mfma_f32_32x32x16_bf16 v[16:31], v[232:235], v[212:215], v[16:31]
	ds_read_b128 v[232:235], v211 offset:54176
	s_waitcnt lgkmcnt(4)
	v_mfma_f32_32x32x16_bf16 v[0:15], v[236:239], v[212:215], v[0:15]
	ds_read_b128 v[236:239], v181 offset:416
	s_waitcnt vmcnt(2) lgkmcnt(4)
	v_mfma_f32_32x32x16_bf16 v[112:127], v[240:243], v[216:219], v[112:127]
	ds_read_b128 v[240:243], v220 offset:416
	s_waitcnt lgkmcnt(4)
	v_mfma_f32_32x32x16_bf16 v[96:111], v[224:227], v[216:219], v[96:111]
	ds_read_b128 v[224:227], v221 offset:416
	s_waitcnt lgkmcnt(4)
	v_mfma_f32_32x32x16_bf16 v[80:95], v[228:231], v[216:219], v[80:95]
	ds_read_b128 v[228:231], v222 offset:416
	s_waitcnt lgkmcnt(4)
	v_mfma_f32_32x32x16_bf16 v[64:79], v[232:235], v[216:219], v[64:79]
	ds_read_b128 v[232:235], v211 offset:448
	s_waitcnt lgkmcnt(4)
	v_mfma_f32_32x32x16_bf16 v[48:63], v[236:239], v[216:219], v[48:63]
	ds_read_b128 v[236:239], v211 offset:18368
	s_waitcnt lgkmcnt(4)
	v_mfma_f32_32x32x16_bf16 v[32:47], v[240:243], v[216:219], v[32:47]
	ds_read_b128 v[240:243], v211 offset:36288
	s_waitcnt lgkmcnt(4)
	v_mfma_f32_32x32x16_bf16 v[16:31], v[224:227], v[216:219], v[16:31]
	ds_read_b128 v[224:227], v211 offset:54208
	s_waitcnt lgkmcnt(4)
	v_mfma_f32_32x32x16_bf16 v[0:15], v[228:231], v[216:219], v[0:15]
	ds_read_b128 v[228:231], v181 offset:448
	s_waitcnt vmcnt(1) lgkmcnt(4)
	v_mfma_f32_32x32x16_bf16 v[112:127], v[232:235], v[248:251], v[112:127]
	ds_read_b128 v[232:235], v220 offset:448
	s_waitcnt lgkmcnt(4)
	v_mfma_f32_32x32x16_bf16 v[96:111], v[236:239], v[248:251], v[96:111]
	ds_read_b128 v[236:239], v221 offset:448
	s_waitcnt lgkmcnt(4)
	v_mfma_f32_32x32x16_bf16 v[80:95], v[240:243], v[248:251], v[80:95]
	ds_read_b128 v[240:243], v222 offset:448
	s_waitcnt lgkmcnt(4)
	v_mfma_f32_32x32x16_bf16 v[64:79], v[224:227], v[248:251], v[64:79]
	ds_read_b128 v[224:227], v211 offset:480
	s_waitcnt lgkmcnt(4)
	v_mfma_f32_32x32x16_bf16 v[48:63], v[228:231], v[248:251], v[48:63]
	ds_read_b128 v[228:231], v211 offset:18400
	s_waitcnt lgkmcnt(4)
	v_mfma_f32_32x32x16_bf16 v[32:47], v[232:235], v[248:251], v[32:47]
	ds_read_b128 v[232:235], v211 offset:36320
	s_waitcnt lgkmcnt(4)
	v_mfma_f32_32x32x16_bf16 v[16:31], v[236:239], v[248:251], v[16:31]
	ds_read_b128 v[236:239], v211 offset:54240
	s_waitcnt lgkmcnt(4)
	v_mfma_f32_32x32x16_bf16 v[0:15], v[240:243], v[248:251], v[0:15]
	ds_read_b128 v[240:243], v181 offset:480
	s_waitcnt vmcnt(0) lgkmcnt(4)
	v_mfma_f32_32x32x16_bf16 v[112:127], v[224:227], v[244:247], v[112:127]
	ds_read_b128 v[224:227], v220 offset:480
	s_waitcnt lgkmcnt(4)
	v_mfma_f32_32x32x16_bf16 v[96:111], v[228:231], v[244:247], v[96:111]
	ds_read_b128 v[228:231], v221 offset:480
	s_waitcnt lgkmcnt(4)
	v_mfma_f32_32x32x16_bf16 v[80:95], v[232:235], v[244:247], v[80:95]
	ds_read_b128 v[232:235], v222 offset:480
	s_waitcnt lgkmcnt(4)
	v_mfma_f32_32x32x16_bf16 v[64:79], v[236:239], v[244:247], v[64:79]
	s_waitcnt lgkmcnt(3)
	v_mfma_f32_32x32x16_bf16 v[48:63], v[240:243], v[244:247], v[48:63]
	s_waitcnt lgkmcnt(2)
	v_mfma_f32_32x32x16_bf16 v[32:47], v[224:227], v[244:247], v[32:47]
	s_waitcnt lgkmcnt(1)
	v_mfma_f32_32x32x16_bf16 v[16:31], v[228:231], v[244:247], v[16:31]
	s_waitcnt lgkmcnt(0)
	v_mfma_f32_32x32x16_bf16 v[0:15], v[232:235], v[244:247], v[0:15]
	s_movk_i32 s47, 0x200
	v_lshl_add_u64 v[244:245], v[160:161], 0, s[38:39]
	global_load_dwordx4 v[212:215], v[160:161], off offset:2096
	global_load_dwordx4 v[216:219], v[160:161], off offset:2080
	global_load_dwordx4 v[224:227], v[160:161], off offset:2064
	global_load_dwordx4 v[228:231], v[160:161], off offset:2048
	global_load_dwordx4 v[232:235], v[168:169], off offset:2048
	global_load_dwordx4 v[236:239], v[244:245], off offset:48
	global_load_dwordx4 v[240:243], v[244:245], off offset:32
	global_load_dwordx4 v[246:249], v[244:245], off offset:16
	v_mov_b32_e32 v170, v145
	v_mov_b32_e32 v171, v146
	v_mov_b32_e32 v145, v147
	v_mov_b32_e32 v146, v141
	v_mov_b32_e32 v147, v142
	v_mov_b32_e32 v141, v143
	v_pk_add_f32 v[144:145], v[170:171], v[144:145]
	v_pk_add_f32 v[140:141], v[146:147], v[140:141]
	v_pk_add_f32 v[144:145], v[144:145], v[144:145] op_sel:[0,1] op_sel_hi:[1,0]
	v_pk_add_f32 v[140:141], v[140:141], v[140:141] op_sel:[0,1] op_sel_hi:[1,0]
	v_add_f32_e32 v136, v136, v137
	v_add_f32_e32 v138, v138, v139
	v_mov_b32_e32 v145, v132
	v_mov_b32_e32 v141, v133
	v_mov_b32_e32 v137, v134
	v_mov_b32_e32 v139, v135
	v_pk_add_f32 v[132:133], v[144:145], v[140:141]
	v_pk_add_f32 v[134:135], v[136:137], v[138:139]
	s_lshl_b32 s10, s46, 1
	v_pk_add_f32 v[132:133], v[132:133], v[134:135]
	v_mov_b32_e32 v159, v149
	v_add_f32_e32 v132, v132, v133
	v_fmamk_f32 v132, v132, 0x3a800000, v180
	v_cmp_gt_f32_e32 vcc, s49, v132
	v_mul_f32_e32 v133, 0x4b800000, v132
	s_add_i32 s51, s51, 1
	v_cndmask_b32_e32 v132, v132, v133, vcc
	v_rsq_f32_e32 v132, v132
	s_nop 0
	v_mul_f32_e32 v133, 0x45800000, v132
	v_cndmask_b32_e32 v134, v132, v133, vcc
	v_mov_b32_e32 v132, v129
	v_mov_b32_e32 v133, v130
	v_mov_b32_e32 v129, v131
	v_pk_add_f32 v[128:129], v[132:133], v[128:129]
	v_and_b32_e32 v131, 64, v178
	v_add_f32_e32 v128, v128, v129
	v_mul_f32_e32 v129, v134, v134
	v_mul_f32_e32 v128, v128, v129
	v_fmamk_f32 v128, v128, 0x3b800000, v180
	v_cmp_gt_f32_e32 vcc, s49, v128
	v_mul_f32_e32 v129, 0x4b800000, v128
	v_add_u32_e32 v131, 64, v131
	v_cndmask_b32_e32 v128, v128, v129, vcc
	v_rsq_f32_e32 v128, v128
	s_nop 0
	v_mul_f32_e32 v129, 0x45800000, v128
	v_cndmask_b32_e32 v128, v128, v129, vcc
	v_max3_f32 v129, v112, s50, v113
	v_max3_f32 v129, v129, v114, v115
	v_max3_f32 v129, v129, v116, v117
	v_max3_f32 v129, v129, v118, v119
	v_max3_f32 v129, v129, v120, v121
	v_max3_f32 v129, v129, v122, v123
	v_max3_f32 v129, v129, v124, v125
	v_max3_f32 v129, v129, v126, v127
	v_max3_f32 v129, v129, v96, v97
	v_max3_f32 v129, v129, v98, v99
	v_max3_f32 v129, v129, v100, v101
	v_max3_f32 v129, v129, v102, v103
	v_max3_f32 v129, v129, v104, v105
	v_max3_f32 v129, v129, v106, v107
	v_max3_f32 v129, v129, v108, v109
	v_max3_f32 v129, v129, v110, v111
	v_max3_f32 v129, v129, v80, v81
	v_max3_f32 v129, v129, v82, v83
	v_max3_f32 v129, v129, v84, v85
	v_max3_f32 v129, v129, v86, v87
	v_max3_f32 v129, v129, v88, v89
	v_max3_f32 v129, v129, v90, v91
	v_max3_f32 v129, v129, v92, v93
	v_max3_f32 v129, v129, v94, v95
	v_max3_f32 v129, v129, v64, v65
	v_max3_f32 v129, v129, v66, v67
	v_max3_f32 v129, v129, v68, v69
	v_max3_f32 v129, v129, v70, v71
	v_max3_f32 v129, v129, v72, v73
	v_max3_f32 v129, v129, v74, v75
	v_max3_f32 v129, v129, v76, v77
	v_max3_f32 v129, v129, v78, v79
	v_max3_f32 v129, v129, v48, v49
	v_max3_f32 v129, v129, v50, v51
	v_max3_f32 v129, v129, v52, v53
	v_max3_f32 v129, v129, v54, v55
	v_max3_f32 v129, v129, v56, v57
	v_max3_f32 v129, v129, v58, v59
	v_max3_f32 v129, v129, v60, v61
	v_max3_f32 v129, v129, v62, v63
	v_max3_f32 v129, v129, v32, v33
	v_max3_f32 v129, v129, v34, v35
	v_max3_f32 v129, v129, v36, v37
	v_max3_f32 v129, v129, v38, v39
	v_max3_f32 v129, v129, v40, v41
	v_max3_f32 v129, v129, v42, v43
	v_max3_f32 v129, v129, v44, v45
	v_max3_f32 v129, v129, v46, v47
	v_max3_f32 v129, v129, v16, v17
	v_max3_f32 v129, v129, v18, v19
	v_max3_f32 v129, v129, v20, v21
	v_max3_f32 v129, v129, v22, v23
	v_max3_f32 v129, v129, v24, v25
	v_max3_f32 v129, v129, v26, v27
	v_max3_f32 v129, v129, v28, v29
	v_max3_f32 v129, v129, v30, v31
	v_max3_f32 v129, v129, v0, v1
	v_max3_f32 v129, v129, v2, v3
	v_max3_f32 v129, v129, v4, v5
	v_max3_f32 v129, v129, v6, v7
	v_max3_f32 v129, v129, v8, v9
	v_max3_f32 v129, v129, v10, v11
	v_mul_f32_e32 v128, v134, v128
	v_max3_f32 v129, v129, v12, v13
	v_max3_f32 v130, v129, v14, v15
	v_mul_f32_e32 v129, 0x3db8aa3b, v128
	v_xor_b32_e32 v128, 32, v178
	v_cmp_lt_i32_e32 vcc, v128, v131
	v_mul_f32_e32 v130, v129, v130
	s_nop 0
	v_cndmask_b32_e32 v128, v178, v128, vcc
	v_lshlrev_b32_e32 v128, 2, v128
	ds_bpermute_b32 v131, v128, v130
	s_waitcnt lgkmcnt(0)
	v_max_f32_e32 v131, v131, v131
	v_max_f32_e32 v130, v130, v131
	v_fma_f32 v112, v129, v112, -v130
	v_exp_f32_e32 v112, v112
	v_fma_f32 v113, v129, v113, -v130
	v_exp_f32_e32 v113, v113
	v_fma_f32 v114, v129, v114, -v130
	v_exp_f32_e32 v114, v114
	v_fma_f32 v115, v129, v115, -v130
	v_exp_f32_e32 v115, v115
	v_fma_f32 v116, v129, v116, -v130
	v_add_f32_e32 v131, 0, v112
	v_exp_f32_e32 v132, v116
	v_add_f32_e32 v131, v113, v131
	v_add_f32_e32 v131, v114, v131
	v_add_f32_e32 v131, v115, v131
	v_fma_f32 v117, v129, v117, -v130
	v_add_f32_e32 v116, v132, v131
	v_exp_f32_e32 v131, v117
	v_fma_f32 v117, v129, v118, -v130
	v_exp_f32_e32 v133, v117
	v_fma_f32 v117, v129, v119, -v130
	v_exp_f32_e32 v119, v117
	v_fma_f32 v117, v129, v120, -v130
	v_exp_f32_e32 v120, v117
	v_fma_f32 v117, v129, v121, -v130
	v_add_f32_e32 v116, v131, v116
	v_exp_f32_e32 v121, v117
	v_fma_f32 v117, v129, v122, -v130
	v_add_f32_e32 v116, v133, v116
	v_exp_f32_e32 v122, v117
	v_fma_f32 v117, v129, v123, -v130
	v_add_f32_e32 v116, v119, v116
	v_exp_f32_e32 v123, v117
	v_fma_f32 v117, v129, v124, -v130
	v_add_f32_e32 v116, v120, v116
	v_exp_f32_e32 v124, v117
	v_fma_f32 v117, v129, v125, -v130
	v_add_f32_e32 v116, v121, v116
	v_exp_f32_e32 v125, v117
	v_fma_f32 v117, v129, v126, -v130
	v_add_f32_e32 v116, v122, v116
	v_exp_f32_e32 v126, v117
	v_fma_f32 v117, v129, v127, -v130
	v_add_f32_e32 v116, v123, v116
	v_exp_f32_e32 v127, v117
	v_fma_f32 v96, v129, v96, -v130
	v_add_f32_e32 v116, v124, v116
	v_exp_f32_e32 v96, v96
	v_fma_f32 v97, v129, v97, -v130
	v_add_f32_e32 v116, v125, v116
	v_exp_f32_e32 v97, v97
	v_fma_f32 v98, v129, v98, -v130
	v_add_f32_e32 v116, v126, v116
	v_exp_f32_e32 v98, v98
	v_fma_f32 v99, v129, v99, -v130
	v_add_f32_e32 v134, v127, v116
	v_exp_f32_e32 v99, v99
	v_fma_f32 v100, v129, v100, -v130
	v_cvt_pk_bf16_f32 v116, v112, v113
	v_cvt_pk_bf16_f32 v112, v120, v121
	v_add_f32_e32 v120, v96, v134
	v_exp_f32_e32 v121, v100
	v_add_f32_e32 v120, v97, v120
	v_add_f32_e32 v120, v98, v120
	v_add_f32_e32 v120, v99, v120
	v_fma_f32 v101, v129, v101, -v130
	v_add_f32_e32 v100, v121, v120
	v_exp_f32_e32 v120, v101
	v_fma_f32 v101, v129, v102, -v130
	v_cvt_pk_bf16_f32 v113, v122, v123
	v_exp_f32_e32 v122, v101
	v_fma_f32 v101, v129, v103, -v130
	v_exp_f32_e32 v103, v101
	v_fma_f32 v101, v129, v104, -v130
	v_exp_f32_e32 v104, v101
	v_fma_f32 v101, v129, v105, -v130
	v_add_f32_e32 v100, v120, v100
	v_exp_f32_e32 v105, v101
	v_fma_f32 v101, v129, v106, -v130
	v_add_f32_e32 v100, v122, v100
	v_exp_f32_e32 v106, v101
	v_fma_f32 v101, v129, v107, -v130
	v_add_f32_e32 v100, v103, v100
	v_exp_f32_e32 v107, v101
	v_fma_f32 v101, v129, v108, -v130
	v_add_f32_e32 v100, v104, v100
	v_exp_f32_e32 v108, v101
	v_fma_f32 v101, v129, v109, -v130
	v_add_f32_e32 v100, v105, v100
	v_exp_f32_e32 v109, v101
	v_fma_f32 v101, v129, v110, -v130
	v_add_f32_e32 v100, v106, v100
	v_exp_f32_e32 v110, v101
	v_fma_f32 v101, v129, v111, -v130
	v_add_f32_e32 v100, v107, v100
	v_exp_f32_e32 v111, v101
	v_fma_f32 v80, v129, v80, -v130
	v_add_f32_e32 v100, v108, v100
	v_exp_f32_e32 v80, v80
	v_fma_f32 v81, v129, v81, -v130
	v_add_f32_e32 v100, v109, v100
	v_exp_f32_e32 v81, v81
	v_fma_f32 v82, v129, v82, -v130
	v_add_f32_e32 v100, v110, v100
	v_exp_f32_e32 v82, v82
	v_fma_f32 v83, v129, v83, -v130
	v_add_f32_e32 v123, v111, v100
	v_exp_f32_e32 v83, v83
	v_fma_f32 v84, v129, v84, -v130
	v_cvt_pk_bf16_f32 v100, v96, v97
	v_cvt_pk_bf16_f32 v96, v104, v105
	v_add_f32_e32 v104, v80, v123
	v_exp_f32_e32 v105, v84
	v_add_f32_e32 v104, v81, v104
	v_add_f32_e32 v104, v82, v104
	v_add_f32_e32 v104, v83, v104
	v_fma_f32 v85, v129, v85, -v130
	v_add_f32_e32 v84, v105, v104
	v_exp_f32_e32 v104, v85
	v_fma_f32 v85, v129, v86, -v130
	v_cvt_pk_bf16_f32 v97, v106, v107
	v_exp_f32_e32 v106, v85
	v_fma_f32 v85, v129, v87, -v130
	v_exp_f32_e32 v87, v85
	v_fma_f32 v85, v129, v88, -v130
	v_exp_f32_e32 v88, v85
	v_fma_f32 v85, v129, v89, -v130
	v_add_f32_e32 v84, v104, v84
	v_exp_f32_e32 v89, v85
	v_fma_f32 v85, v129, v90, -v130
	v_add_f32_e32 v84, v106, v84
	v_exp_f32_e32 v90, v85
	v_fma_f32 v85, v129, v91, -v130
	v_add_f32_e32 v84, v87, v84
	v_exp_f32_e32 v91, v85
	v_fma_f32 v85, v129, v92, -v130
	v_add_f32_e32 v84, v88, v84
	v_exp_f32_e32 v92, v85
	v_fma_f32 v85, v129, v93, -v130
	v_add_f32_e32 v84, v89, v84
	v_exp_f32_e32 v93, v85
	v_fma_f32 v85, v129, v94, -v130
	v_add_f32_e32 v84, v90, v84
	v_exp_f32_e32 v94, v85
	v_fma_f32 v85, v129, v95, -v130
	v_add_f32_e32 v84, v91, v84
	v_exp_f32_e32 v95, v85
	v_fma_f32 v64, v129, v64, -v130
	v_add_f32_e32 v84, v92, v84
	v_exp_f32_e32 v64, v64
	v_fma_f32 v65, v129, v65, -v130
	v_add_f32_e32 v84, v93, v84
	v_exp_f32_e32 v65, v65
	v_fma_f32 v66, v129, v66, -v130
	v_add_f32_e32 v84, v94, v84
	v_exp_f32_e32 v66, v66
	v_fma_f32 v67, v129, v67, -v130
	v_add_f32_e32 v107, v95, v84
	v_exp_f32_e32 v67, v67
	v_fma_f32 v68, v129, v68, -v130
	v_cvt_pk_bf16_f32 v84, v80, v81
	v_cvt_pk_bf16_f32 v80, v88, v89
	v_add_f32_e32 v88, v64, v107
	v_exp_f32_e32 v89, v68
	v_add_f32_e32 v88, v65, v88
	v_add_f32_e32 v88, v66, v88
	v_add_f32_e32 v88, v67, v88
	v_fma_f32 v69, v129, v69, -v130
	v_add_f32_e32 v68, v89, v88
	v_exp_f32_e32 v88, v69
	v_fma_f32 v69, v129, v70, -v130
	v_cvt_pk_bf16_f32 v81, v90, v91
	v_exp_f32_e32 v90, v69
	v_fma_f32 v69, v129, v71, -v130
	v_exp_f32_e32 v71, v69
	v_fma_f32 v69, v129, v72, -v130
	v_exp_f32_e32 v72, v69
	v_fma_f32 v69, v129, v73, -v130
	v_add_f32_e32 v68, v88, v68
	v_exp_f32_e32 v73, v69
	v_fma_f32 v69, v129, v74, -v130
	v_add_f32_e32 v68, v90, v68
	v_exp_f32_e32 v74, v69
	v_fma_f32 v69, v129, v75, -v130
	v_add_f32_e32 v68, v71, v68
	v_exp_f32_e32 v75, v69
	v_fma_f32 v69, v129, v76, -v130
	v_add_f32_e32 v68, v72, v68
	v_exp_f32_e32 v76, v69
	v_fma_f32 v69, v129, v77, -v130
	v_add_f32_e32 v68, v73, v68
	v_exp_f32_e32 v77, v69
	v_fma_f32 v69, v129, v78, -v130
	v_add_f32_e32 v68, v74, v68
	v_exp_f32_e32 v78, v69
	v_fma_f32 v69, v129, v79, -v130
	v_add_f32_e32 v68, v75, v68
	v_exp_f32_e32 v79, v69
	v_fma_f32 v48, v129, v48, -v130
	v_add_f32_e32 v68, v76, v68
	v_exp_f32_e32 v48, v48
	v_fma_f32 v49, v129, v49, -v130
	v_add_f32_e32 v68, v77, v68
	v_exp_f32_e32 v49, v49
	v_fma_f32 v50, v129, v50, -v130
	v_add_f32_e32 v68, v78, v68
	v_exp_f32_e32 v50, v50
	v_fma_f32 v51, v129, v51, -v130
	v_add_f32_e32 v91, v79, v68
	v_exp_f32_e32 v51, v51
	v_fma_f32 v52, v129, v52, -v130
	v_cvt_pk_bf16_f32 v68, v64, v65
	v_cvt_pk_bf16_f32 v64, v72, v73
	v_add_f32_e32 v72, v48, v91
	v_exp_f32_e32 v73, v52
	v_add_f32_e32 v72, v49, v72
	v_add_f32_e32 v72, v50, v72
	v_add_f32_e32 v72, v51, v72
	v_fma_f32 v53, v129, v53, -v130
	v_add_f32_e32 v52, v73, v72
	v_exp_f32_e32 v72, v53
	v_fma_f32 v53, v129, v54, -v130
	v_cvt_pk_bf16_f32 v65, v74, v75
	v_exp_f32_e32 v74, v53
	v_fma_f32 v53, v129, v55, -v130
	v_exp_f32_e32 v55, v53
	v_fma_f32 v53, v129, v56, -v130
	v_exp_f32_e32 v56, v53
	v_fma_f32 v53, v129, v57, -v130
	v_add_f32_e32 v52, v72, v52
	v_exp_f32_e32 v57, v53
	v_fma_f32 v53, v129, v58, -v130
	v_add_f32_e32 v52, v74, v52
	v_exp_f32_e32 v58, v53
	v_fma_f32 v53, v129, v59, -v130
	v_add_f32_e32 v52, v55, v52
	v_exp_f32_e32 v59, v53
	v_fma_f32 v53, v129, v60, -v130
	v_add_f32_e32 v52, v56, v52
	v_exp_f32_e32 v60, v53
	v_fma_f32 v53, v129, v61, -v130
	v_add_f32_e32 v52, v57, v52
	v_exp_f32_e32 v61, v53
	v_fma_f32 v53, v129, v62, -v130
	v_add_f32_e32 v52, v58, v52
	v_exp_f32_e32 v62, v53
	v_fma_f32 v53, v129, v63, -v130
	v_add_f32_e32 v52, v59, v52
	v_exp_f32_e32 v63, v53
	v_fma_f32 v32, v129, v32, -v130
	v_add_f32_e32 v52, v60, v52
	v_exp_f32_e32 v32, v32
	v_fma_f32 v33, v129, v33, -v130
	v_add_f32_e32 v52, v61, v52
	v_exp_f32_e32 v33, v33
	v_fma_f32 v34, v129, v34, -v130
	v_add_f32_e32 v52, v62, v52
	v_exp_f32_e32 v34, v34
	v_fma_f32 v35, v129, v35, -v130
	v_add_f32_e32 v75, v63, v52
	v_exp_f32_e32 v35, v35
	v_fma_f32 v36, v129, v36, -v130
	v_cvt_pk_bf16_f32 v52, v48, v49
	v_cvt_pk_bf16_f32 v48, v56, v57
	v_add_f32_e32 v56, v32, v75
	v_exp_f32_e32 v57, v36
	v_add_f32_e32 v56, v33, v56
	v_add_f32_e32 v56, v34, v56
	v_add_f32_e32 v56, v35, v56
	v_fma_f32 v37, v129, v37, -v130
	v_add_f32_e32 v36, v57, v56
	v_exp_f32_e32 v56, v37
	v_fma_f32 v37, v129, v38, -v130
	v_cvt_pk_bf16_f32 v49, v58, v59
	v_exp_f32_e32 v58, v37
	v_fma_f32 v37, v129, v39, -v130
	v_exp_f32_e32 v39, v37
	v_fma_f32 v37, v129, v40, -v130
	v_exp_f32_e32 v40, v37
	v_fma_f32 v37, v129, v41, -v130
	v_add_f32_e32 v36, v56, v36
	v_exp_f32_e32 v41, v37
	v_fma_f32 v37, v129, v42, -v130
	v_add_f32_e32 v36, v58, v36
	v_exp_f32_e32 v42, v37
	v_fma_f32 v37, v129, v43, -v130
	v_add_f32_e32 v36, v39, v36
	v_exp_f32_e32 v43, v37
	v_fma_f32 v37, v129, v44, -v130
	v_add_f32_e32 v36, v40, v36
	v_exp_f32_e32 v44, v37
	v_fma_f32 v37, v129, v45, -v130
	v_add_f32_e32 v36, v41, v36
	v_exp_f32_e32 v45, v37
	v_fma_f32 v37, v129, v46, -v130
	v_add_f32_e32 v36, v42, v36
	v_exp_f32_e32 v46, v37
	v_fma_f32 v37, v129, v47, -v130
	v_add_f32_e32 v36, v43, v36
	v_exp_f32_e32 v47, v37
	v_fma_f32 v16, v129, v16, -v130
	v_add_f32_e32 v36, v44, v36
	v_exp_f32_e32 v16, v16
	v_fma_f32 v17, v129, v17, -v130
	v_add_f32_e32 v36, v45, v36
	v_exp_f32_e32 v17, v17
	v_fma_f32 v18, v129, v18, -v130
	v_add_f32_e32 v36, v46, v36
	v_exp_f32_e32 v18, v18
	v_fma_f32 v19, v129, v19, -v130
	v_add_f32_e32 v59, v47, v36
	v_exp_f32_e32 v19, v19
	v_fma_f32 v20, v129, v20, -v130
	v_cvt_pk_bf16_f32 v36, v32, v33
	v_cvt_pk_bf16_f32 v32, v40, v41
	v_add_f32_e32 v40, v16, v59
	v_exp_f32_e32 v41, v20
	v_add_f32_e32 v40, v17, v40
	v_add_f32_e32 v40, v18, v40
	v_add_f32_e32 v40, v19, v40
	v_fma_f32 v21, v129, v21, -v130
	v_add_f32_e32 v20, v41, v40
	v_exp_f32_e32 v40, v21
	v_fma_f32 v21, v129, v22, -v130
	v_cvt_pk_bf16_f32 v33, v42, v43
	v_exp_f32_e32 v42, v21
	v_fma_f32 v21, v129, v23, -v130
	v_exp_f32_e32 v23, v21
	v_fma_f32 v21, v129, v24, -v130
	v_exp_f32_e32 v24, v21
	v_fma_f32 v21, v129, v25, -v130
	v_add_f32_e32 v20, v40, v20
	v_exp_f32_e32 v25, v21
	v_fma_f32 v21, v129, v26, -v130
	v_add_f32_e32 v20, v42, v20
	v_exp_f32_e32 v26, v21
	v_fma_f32 v21, v129, v27, -v130
	v_add_f32_e32 v20, v23, v20
	v_exp_f32_e32 v27, v21
	v_fma_f32 v21, v129, v28, -v130
	v_add_f32_e32 v20, v24, v20
	v_exp_f32_e32 v28, v21
	v_fma_f32 v21, v129, v29, -v130
	v_add_f32_e32 v20, v25, v20
	v_exp_f32_e32 v29, v21
	v_fma_f32 v21, v129, v30, -v130
	v_add_f32_e32 v20, v26, v20
	v_exp_f32_e32 v30, v21
	v_fma_f32 v21, v129, v31, -v130
	v_add_f32_e32 v20, v27, v20
	v_exp_f32_e32 v31, v21
	v_fma_f32 v0, v129, v0, -v130
	v_add_f32_e32 v20, v28, v20
	v_exp_f32_e32 v0, v0
	v_fma_f32 v1, v129, v1, -v130
	v_add_f32_e32 v20, v29, v20
	v_exp_f32_e32 v1, v1
	v_fma_f32 v2, v129, v2, -v130
	v_add_f32_e32 v20, v30, v20
	v_exp_f32_e32 v2, v2
	v_fma_f32 v3, v129, v3, -v130
	v_add_f32_e32 v43, v31, v20
	v_exp_f32_e32 v3, v3
	v_fma_f32 v4, v129, v4, -v130
	v_cvt_pk_bf16_f32 v20, v16, v17
	v_cvt_pk_bf16_f32 v16, v24, v25
	v_add_f32_e32 v24, v0, v43
	v_exp_f32_e32 v4, v4
	v_fma_f32 v5, v129, v5, -v130
	v_add_f32_e32 v24, v1, v24
	v_exp_f32_e32 v5, v5
	v_fma_f32 v6, v129, v6, -v130
	v_add_f32_e32 v24, v2, v24
	v_exp_f32_e32 v6, v6
	v_fma_f32 v7, v129, v7, -v130
	v_add_f32_e32 v24, v3, v24
	v_exp_f32_e32 v7, v7
	v_fma_f32 v8, v129, v8, -v130
	v_add_f32_e32 v24, v4, v24
	v_exp_f32_e32 v8, v8
	v_fma_f32 v9, v129, v9, -v130
	v_add_f32_e32 v24, v5, v24
	v_exp_f32_e32 v9, v9
	v_fma_f32 v10, v129, v10, -v130
	v_add_f32_e32 v24, v6, v24
	v_exp_f32_e32 v10, v10
	v_fma_f32 v11, v129, v11, -v130
	v_add_f32_e32 v24, v7, v24
	v_exp_f32_e32 v11, v11
	v_fma_f32 v12, v129, v12, -v130
	v_add_f32_e32 v24, v8, v24
	v_exp_f32_e32 v12, v12
	v_fma_f32 v13, v129, v13, -v130
	v_add_f32_e32 v24, v9, v24
	v_exp_f32_e32 v13, v13
	v_fma_f32 v14, v129, v14, -v130
	v_add_f32_e32 v24, v10, v24
	v_exp_f32_e32 v14, v14
	v_fma_f32 v15, v129, v15, -v130
	v_add_f32_e32 v24, v11, v24
	v_exp_f32_e32 v15, v15
	v_add_f32_e32 v24, v12, v24
	v_add_f32_e32 v24, v13, v24
	v_add_f32_e32 v24, v14, v24
	v_cvt_pk_bf16_f32 v22, v41, v40
	v_add_f32_e32 v40, v15, v24
	v_cvt_pk_bf16_f32 v21, v18, v19
	v_cvt_pk_bf16_f32 v18, v28, v29
	v_cvt_pk_bf16_f32 v28, v0, v1
	ds_bpermute_b32 v0, v128, v40
	v_cvt_pk_bf16_f32 v117, v114, v115
	v_cvt_pk_bf16_f32 v118, v132, v131
	v_cvt_pk_bf16_f32 v119, v133, v119
	v_cvt_pk_bf16_f32 v114, v124, v125
	v_cvt_pk_bf16_f32 v115, v126, v127
	v_cvt_pk_bf16_f32 v101, v98, v99
	v_cvt_pk_bf16_f32 v102, v121, v120
	v_cvt_pk_bf16_f32 v103, v122, v103
	v_cvt_pk_bf16_f32 v98, v108, v109
	v_cvt_pk_bf16_f32 v99, v110, v111
	v_cvt_pk_bf16_f32 v85, v82, v83
	v_cvt_pk_bf16_f32 v86, v105, v104
	v_cvt_pk_bf16_f32 v87, v106, v87
	v_cvt_pk_bf16_f32 v82, v92, v93
	v_cvt_pk_bf16_f32 v83, v94, v95
	v_cvt_pk_bf16_f32 v69, v66, v67
	v_cvt_pk_bf16_f32 v70, v89, v88
	v_cvt_pk_bf16_f32 v71, v90, v71
	v_cvt_pk_bf16_f32 v66, v76, v77
	v_cvt_pk_bf16_f32 v67, v78, v79
	v_cvt_pk_bf16_f32 v53, v50, v51
	v_cvt_pk_bf16_f32 v54, v73, v72
	v_cvt_pk_bf16_f32 v55, v74, v55
	v_cvt_pk_bf16_f32 v50, v60, v61
	v_cvt_pk_bf16_f32 v51, v62, v63
	v_cvt_pk_bf16_f32 v37, v34, v35
	v_cvt_pk_bf16_f32 v38, v57, v56
	v_cvt_pk_bf16_f32 v39, v58, v39
	v_cvt_pk_bf16_f32 v34, v44, v45
	v_cvt_pk_bf16_f32 v35, v46, v47
	v_cvt_pk_bf16_f32 v23, v42, v23
	v_cvt_pk_bf16_f32 v17, v26, v27
	v_cvt_pk_bf16_f32 v19, v30, v31
	v_cvt_pk_bf16_f32 v29, v2, v3
	v_cvt_pk_bf16_f32 v30, v4, v5
	v_cvt_pk_bf16_f32 v31, v6, v7
	v_cvt_pk_bf16_f32 v24, v8, v9
	v_cvt_pk_bf16_f32 v25, v10, v11
	v_cvt_pk_bf16_f32 v26, v12, v13
	v_cvt_pk_bf16_f32 v27, v14, v15
	v_lshl_add_u64 v[60:61], v[160:161], 0, s[38:39]
	s_waitcnt lgkmcnt(0)
	v_add_f32_e32 v72, v40, v0
	s_barrier
	s_waitcnt vmcnt(0)
	ds_write_b128 v172, v[228:231]
	ds_write_b128 v172, v[224:227] offset:16
	ds_write_b128 v172, v[216:219] offset:32
	ds_write_b128 v172, v[212:215] offset:48
	ds_write_b128 v172, v[232:235] offset:35840
	ds_write_b128 v172, v[246:249] offset:35856
	ds_write_b128 v172, v[240:243] offset:35872
	ds_write_b128 v172, v[236:239] offset:35888
	v_lshl_add_u64 v[12:13], v[160:161], 0, s[40:41]
	v_lshl_add_u64 v[60:61], v[160:161], 0, s[44:45]
	global_load_dwordx4 v[0:3], v[164:165], off offset:2048
	global_load_dwordx4 v[4:7], v[12:13], off offset:48
	global_load_dwordx4 v[8:11], v[12:13], off offset:32
	s_nop 0
	global_load_dwordx4 v[12:15], v[12:13], off offset:16
	s_nop 0
	global_load_dwordx4 v[40:43], v[166:167], off offset:2048
	global_load_dwordx4 v[44:47], v[60:61], off offset:48
	global_load_dwordx4 v[56:59], v[60:61], off offset:32
	s_nop 0
	global_load_dwordx4 v[60:63], v[60:61], off offset:16
	s_waitcnt vmcnt(7)
	ds_write_b128 v173, v[0:3]
	s_waitcnt vmcnt(4)
	ds_write_b128 v174, v[12:15]
	ds_write_b128 v175, v[8:11]
	ds_write_b128 v179, v[4:7]
	s_waitcnt vmcnt(3)
	ds_write_b128 v182, v[40:43]
	s_waitcnt vmcnt(0)
	ds_write_b128 v183, v[60:63]
	ds_write_b128 v184, v[56:59]
	ds_write_b128 v185, v[44:47]
	v_div_scale_f32 v0, s[4:5], v72, v72, 1.0
	v_rcp_f32_e32 v1, v0
	s_waitcnt lgkmcnt(0)
	s_barrier
	v_fma_f32 v2, -v0, v1, 1.0
	v_fmac_f32_e32 v1, v2, v1
	v_div_scale_f32 v2, vcc, 1.0, v72, 1.0
	v_mul_f32_e32 v3, v2, v1
	v_fma_f32 v4, -v0, v3, v2
	v_fmac_f32_e32 v3, v4, v1
	v_fma_f32 v0, -v0, v3, v2
	v_div_fmas_f32 v0, v0, v1, v3
	v_div_fixup_f32 v44, v0, v72, 1.0
	v_lshl_add_u64 v[0:1], s[12:13], 0, v[162:163]
	v_lshl_add_u64 v[0:1], v[0:1], 0, s[10:11]
	v_lshl_add_u64 v[46:47], v[0:1], 0, v[158:159]
	v_mbcnt_lo_u32_b32 v40, -1, 0
	v_mbcnt_hi_u32_b32 v40, -1, v40
	v_and_b32_e32 v40, 32, v40
	v_lshrrev_b32_e32 v40, 2, v40
	v_mov_b32_e32 v41, 0
	v_lshl_add_u64 v[124:125], v[46:47], 0, v[40:41]
	ds_read_b64_tr_b16 v[56:57], v186
	ds_read_b64_tr_b16 v[58:59], v186 offset:4480
	ds_read_b64_tr_b16 v[60:61], v186 offset:8960
	ds_read_b64_tr_b16 v[62:63], v186 offset:13440
	ds_read_b64_tr_b16 v[88:89], v186 offset:17920
	ds_read_b64_tr_b16 v[90:91], v186 offset:22400
	ds_read_b64_tr_b16 v[92:93], v186 offset:26880
	ds_read_b64_tr_b16 v[94:95], v186 offset:31360
	ds_read_b64_tr_b16 v[104:105], v186 offset:35840
	ds_read_b64_tr_b16 v[106:107], v186 offset:40320
	ds_read_b64_tr_b16 v[108:109], v186 offset:44800
	ds_read_b64_tr_b16 v[110:111], v186 offset:49280
	ds_read_b64_tr_b16 v[120:121], v186 offset:53760
	ds_read_b64_tr_b16 v[122:123], v186 offset:58240
	s_mov_b64 s[4:5], 0
	s_waitcnt lgkmcnt(12)
	v_mfma_f32_32x32x16_bf16 v[0:15], v[56:59], v[116:119], 0
	v_add_u32_e32 v40, v187, v177
	ds_read_b64_tr_b16 v[56:57], v186 offset:62720
	ds_read_b64_tr_b16 v[58:59], v40
	s_waitcnt lgkmcnt(12)
	v_mfma_f32_32x32x16_bf16 v[0:15], v[60:63], v[112:115], v[0:15]
	v_add_u32_e32 v40, v188, v177
	v_add_u32_e32 v42, v189, v177
	ds_read_b64_tr_b16 v[60:61], v40
	ds_read_b64_tr_b16 v[62:63], v42
	s_waitcnt lgkmcnt(12)
	v_mfma_f32_32x32x16_bf16 v[0:15], v[88:91], v[100:103], v[0:15]
	v_add_u32_e32 v40, v190, v177
	v_add_u32_e32 v42, v191, v177
	ds_read_b64_tr_b16 v[88:89], v40
	ds_read_b64_tr_b16 v[90:91], v42
	s_waitcnt lgkmcnt(12)
	v_mfma_f32_32x32x16_bf16 v[0:15], v[92:95], v[96:99], v[0:15]
	v_add_u32_e32 v40, v192, v177
	v_add_u32_e32 v42, v193, v177
	ds_read_b64_tr_b16 v[92:93], v40
	ds_read_b64_tr_b16 v[94:95], v42
	s_waitcnt lgkmcnt(12)
	v_mfma_f32_32x32x16_bf16 v[0:15], v[104:107], v[84:87], v[0:15]
	v_add_u32_e32 v40, v194, v177
	v_add_u32_e32 v42, v195, v177
	ds_read_b64_tr_b16 v[104:105], v40
	ds_read_b64_tr_b16 v[106:107], v42
	s_waitcnt lgkmcnt(12)
	v_mfma_f32_32x32x16_bf16 v[0:15], v[108:111], v[80:83], v[0:15]
	v_add_u32_e32 v40, v196, v177
	v_add_u32_e32 v42, v197, v177
	ds_read_b64_tr_b16 v[108:109], v40
	ds_read_b64_tr_b16 v[110:111], v42
	s_waitcnt lgkmcnt(12)
	v_mfma_f32_32x32x16_bf16 v[0:15], v[120:123], v[68:71], v[0:15]
	v_add_u32_e32 v40, v198, v177
	v_add_u32_e32 v42, v199, v177
	ds_read_b64_tr_b16 v[120:121], v40
	ds_read_b64_tr_b16 v[122:123], v42
	s_waitcnt lgkmcnt(12)
	v_mfma_f32_32x32x16_bf16 v[0:15], v[56:59], v[64:67], v[0:15]
	v_add_u32_e32 v40, v200, v177
	v_add_u32_e32 v42, v201, v177
	ds_read_b64_tr_b16 v[56:57], v40
	ds_read_b64_tr_b16 v[58:59], v42
	s_waitcnt lgkmcnt(12)
	v_mfma_f32_32x32x16_bf16 v[0:15], v[60:63], v[52:55], v[0:15]
	v_add_u32_e32 v40, v202, v177
	v_add_u32_e32 v42, v203, v177
	ds_read_b64_tr_b16 v[60:61], v40
	ds_read_b64_tr_b16 v[62:63], v42
	s_waitcnt lgkmcnt(12)
	v_mfma_f32_32x32x16_bf16 v[0:15], v[88:91], v[48:51], v[0:15]
	ds_read_b64_tr_b16 v[88:89], v186 offset:64
	ds_read_b64_tr_b16 v[90:91], v186 offset:4544
	s_waitcnt lgkmcnt(12)
	v_mfma_f32_32x32x16_bf16 v[0:15], v[92:95], v[36:39], v[0:15]
	ds_read_b64_tr_b16 v[92:93], v186 offset:9024
	ds_read_b64_tr_b16 v[94:95], v186 offset:13504
	s_waitcnt lgkmcnt(12)
	v_mfma_f32_32x32x16_bf16 v[0:15], v[104:107], v[32:35], v[0:15]
	ds_read_b64_tr_b16 v[104:105], v186 offset:17984
	ds_read_b64_tr_b16 v[106:107], v186 offset:22464
	s_waitcnt lgkmcnt(12)
	v_mfma_f32_32x32x16_bf16 v[0:15], v[108:111], v[20:23], v[0:15]
	ds_read_b64_tr_b16 v[108:109], v186 offset:26944
	ds_read_b64_tr_b16 v[110:111], v186 offset:31424
	s_waitcnt lgkmcnt(12)
	v_mfma_f32_32x32x16_bf16 v[0:15], v[120:123], v[16:19], v[0:15]
	ds_read_b64_tr_b16 v[120:121], v186 offset:35904
	ds_read_b64_tr_b16 v[122:123], v186 offset:40384
	s_waitcnt lgkmcnt(12)
	v_mfma_f32_32x32x16_bf16 v[0:15], v[56:59], v[28:31], v[0:15]
	ds_read_b64_tr_b16 v[56:57], v186 offset:44864
	ds_read_b64_tr_b16 v[58:59], v186 offset:49344
	s_waitcnt lgkmcnt(12)
	v_mfma_f32_32x32x16_bf16 v[0:15], v[60:63], v[24:27], v[0:15]
	ds_read_b64_tr_b16 v[60:61], v186 offset:53824
	ds_read_b64_tr_b16 v[62:63], v186 offset:58304
	s_nop 11
	v_pk_mul_f32 v[0:1], v[0:1], v[44:45] op_sel_hi:[1,0]
	v_pk_mul_f32 v[2:3], v[2:3], v[44:45] op_sel_hi:[1,0]
	v_pk_mul_f32 v[4:5], v[4:5], v[44:45] op_sel_hi:[1,0]
	v_pk_mul_f32 v[6:7], v[6:7], v[44:45] op_sel_hi:[1,0]
	v_cvt_pk_bf16_f32 v0, v0, v1
	v_cvt_pk_bf16_f32 v1, v2, v3
	v_cvt_pk_bf16_f32 v2, v4, v5
	v_cvt_pk_bf16_f32 v3, v6, v7
	s_nop 1
	v_permlane32_swap_b32_e32 v0, v2
	v_permlane32_swap_b32_e32 v1, v3
	global_store_dwordx4 v[124:125], v[0:3], off
	v_pk_mul_f32 v[8:9], v[8:9], v[44:45] op_sel_hi:[1,0]
	v_pk_mul_f32 v[10:11], v[10:11], v[44:45] op_sel_hi:[1,0]
	v_pk_mul_f32 v[12:13], v[12:13], v[44:45] op_sel_hi:[1,0]
	v_pk_mul_f32 v[14:15], v[14:15], v[44:45] op_sel_hi:[1,0]
	v_cvt_pk_bf16_f32 v4, v8, v9
	v_cvt_pk_bf16_f32 v5, v10, v11
	v_cvt_pk_bf16_f32 v6, v12, v13
	v_cvt_pk_bf16_f32 v7, v14, v15
	s_nop 1
	v_permlane32_swap_b32_e32 v4, v6
	v_permlane32_swap_b32_e32 v5, v7
	global_store_dwordx4 v[124:125], v[4:7], off offset:32
	s_nop 1
	s_waitcnt lgkmcnt(12)
	v_mfma_f32_32x32x16_bf16 v[0:15], v[88:91], v[116:119], 0
	v_add_u32_e32 v40, v187, v204
	ds_read_b64_tr_b16 v[88:89], v186 offset:62784
	ds_read_b64_tr_b16 v[90:91], v40
	s_waitcnt lgkmcnt(12)
	v_mfma_f32_32x32x16_bf16 v[0:15], v[92:95], v[112:115], v[0:15]
	v_add_u32_e32 v40, v188, v204
	v_add_u32_e32 v42, v189, v204
	ds_read_b64_tr_b16 v[92:93], v40
	ds_read_b64_tr_b16 v[94:95], v42
	s_waitcnt lgkmcnt(12)
	v_mfma_f32_32x32x16_bf16 v[0:15], v[104:107], v[100:103], v[0:15]
	v_add_u32_e32 v40, v190, v204
	v_add_u32_e32 v42, v191, v204
	ds_read_b64_tr_b16 v[104:105], v40
	ds_read_b64_tr_b16 v[106:107], v42
	s_waitcnt lgkmcnt(12)
	v_mfma_f32_32x32x16_bf16 v[0:15], v[108:111], v[96:99], v[0:15]
	v_add_u32_e32 v40, v192, v204
	v_add_u32_e32 v42, v193, v204
	ds_read_b64_tr_b16 v[108:109], v40
	ds_read_b64_tr_b16 v[110:111], v42
	s_waitcnt lgkmcnt(12)
	v_mfma_f32_32x32x16_bf16 v[0:15], v[120:123], v[84:87], v[0:15]
	v_add_u32_e32 v40, v194, v204
	v_add_u32_e32 v42, v195, v204
	ds_read_b64_tr_b16 v[120:121], v40
	ds_read_b64_tr_b16 v[122:123], v42
	s_waitcnt lgkmcnt(12)
	v_mfma_f32_32x32x16_bf16 v[0:15], v[56:59], v[80:83], v[0:15]
	v_add_u32_e32 v40, v196, v204
	v_add_u32_e32 v42, v197, v204
	ds_read_b64_tr_b16 v[56:57], v40
	ds_read_b64_tr_b16 v[58:59], v42
	s_waitcnt lgkmcnt(12)
	v_mfma_f32_32x32x16_bf16 v[0:15], v[60:63], v[68:71], v[0:15]
	v_add_u32_e32 v40, v198, v204
	v_add_u32_e32 v42, v199, v204
	ds_read_b64_tr_b16 v[60:61], v40
	ds_read_b64_tr_b16 v[62:63], v42
	s_waitcnt lgkmcnt(12)
	v_mfma_f32_32x32x16_bf16 v[0:15], v[88:91], v[64:67], v[0:15]
	v_add_u32_e32 v40, v200, v204
	v_add_u32_e32 v42, v201, v204
	ds_read_b64_tr_b16 v[88:89], v40
	ds_read_b64_tr_b16 v[90:91], v42
	s_waitcnt lgkmcnt(12)
	v_mfma_f32_32x32x16_bf16 v[0:15], v[92:95], v[52:55], v[0:15]
	v_add_u32_e32 v40, v202, v204
	v_add_u32_e32 v42, v203, v204
	ds_read_b64_tr_b16 v[92:93], v40
	ds_read_b64_tr_b16 v[94:95], v42
	s_waitcnt lgkmcnt(12)
	v_mfma_f32_32x32x16_bf16 v[0:15], v[104:107], v[48:51], v[0:15]
	ds_read_b64_tr_b16 v[104:105], v186 offset:128
	ds_read_b64_tr_b16 v[106:107], v186 offset:4608
	s_waitcnt lgkmcnt(12)
	v_mfma_f32_32x32x16_bf16 v[0:15], v[108:111], v[36:39], v[0:15]
	ds_read_b64_tr_b16 v[108:109], v186 offset:9088
	ds_read_b64_tr_b16 v[110:111], v186 offset:13568
	s_waitcnt lgkmcnt(12)
	v_mfma_f32_32x32x16_bf16 v[0:15], v[120:123], v[32:35], v[0:15]
	ds_read_b64_tr_b16 v[120:121], v186 offset:18048
	ds_read_b64_tr_b16 v[122:123], v186 offset:22528
	s_waitcnt lgkmcnt(12)
	v_mfma_f32_32x32x16_bf16 v[0:15], v[56:59], v[20:23], v[0:15]
	ds_read_b64_tr_b16 v[56:57], v186 offset:27008
	ds_read_b64_tr_b16 v[58:59], v186 offset:31488
	s_waitcnt lgkmcnt(12)
	v_mfma_f32_32x32x16_bf16 v[0:15], v[60:63], v[16:19], v[0:15]
	ds_read_b64_tr_b16 v[60:61], v186 offset:35968
	ds_read_b64_tr_b16 v[62:63], v186 offset:40448
	s_waitcnt lgkmcnt(12)
	v_mfma_f32_32x32x16_bf16 v[0:15], v[88:91], v[28:31], v[0:15]
	ds_read_b64_tr_b16 v[88:89], v186 offset:44928
	ds_read_b64_tr_b16 v[90:91], v186 offset:49408
	s_waitcnt lgkmcnt(12)
	v_mfma_f32_32x32x16_bf16 v[0:15], v[92:95], v[24:27], v[0:15]
	ds_read_b64_tr_b16 v[92:93], v186 offset:53888
	ds_read_b64_tr_b16 v[94:95], v186 offset:58368
	s_nop 11
	v_pk_mul_f32 v[0:1], v[0:1], v[44:45] op_sel_hi:[1,0]
	v_pk_mul_f32 v[2:3], v[2:3], v[44:45] op_sel_hi:[1,0]
	v_pk_mul_f32 v[4:5], v[4:5], v[44:45] op_sel_hi:[1,0]
	v_pk_mul_f32 v[6:7], v[6:7], v[44:45] op_sel_hi:[1,0]
	v_cvt_pk_bf16_f32 v0, v0, v1
	v_cvt_pk_bf16_f32 v1, v2, v3
	v_cvt_pk_bf16_f32 v2, v4, v5
	v_cvt_pk_bf16_f32 v3, v6, v7
	s_nop 1
	v_permlane32_swap_b32_e32 v0, v2
	v_permlane32_swap_b32_e32 v1, v3
	global_store_dwordx4 v[124:125], v[0:3], off offset:64
	v_pk_mul_f32 v[8:9], v[8:9], v[44:45] op_sel_hi:[1,0]
	v_pk_mul_f32 v[10:11], v[10:11], v[44:45] op_sel_hi:[1,0]
	v_pk_mul_f32 v[12:13], v[12:13], v[44:45] op_sel_hi:[1,0]
	v_pk_mul_f32 v[14:15], v[14:15], v[44:45] op_sel_hi:[1,0]
	v_cvt_pk_bf16_f32 v4, v8, v9
	v_cvt_pk_bf16_f32 v5, v10, v11
	v_cvt_pk_bf16_f32 v6, v12, v13
	v_cvt_pk_bf16_f32 v7, v14, v15
	s_nop 1
	v_permlane32_swap_b32_e32 v4, v6
	v_permlane32_swap_b32_e32 v5, v7
	global_store_dwordx4 v[124:125], v[4:7], off offset:96
	s_nop 1
	s_waitcnt lgkmcnt(12)
	v_mfma_f32_32x32x16_bf16 v[0:15], v[104:107], v[116:119], 0
	v_add_u32_e32 v40, v187, v205
	ds_read_b64_tr_b16 v[104:105], v186 offset:62848
	ds_read_b64_tr_b16 v[106:107], v40
	s_waitcnt lgkmcnt(12)
	v_mfma_f32_32x32x16_bf16 v[0:15], v[108:111], v[112:115], v[0:15]
	v_add_u32_e32 v40, v188, v205
	v_add_u32_e32 v42, v189, v205
	ds_read_b64_tr_b16 v[108:109], v40
	ds_read_b64_tr_b16 v[110:111], v42
	s_waitcnt lgkmcnt(12)
	v_mfma_f32_32x32x16_bf16 v[0:15], v[120:123], v[100:103], v[0:15]
	v_add_u32_e32 v40, v190, v205
	v_add_u32_e32 v42, v191, v205
	ds_read_b64_tr_b16 v[120:121], v40
	ds_read_b64_tr_b16 v[122:123], v42
	s_waitcnt lgkmcnt(12)
	v_mfma_f32_32x32x16_bf16 v[0:15], v[56:59], v[96:99], v[0:15]
	v_add_u32_e32 v40, v192, v205
	v_add_u32_e32 v42, v193, v205
	ds_read_b64_tr_b16 v[56:57], v40
	ds_read_b64_tr_b16 v[58:59], v42
	s_waitcnt lgkmcnt(12)
	v_mfma_f32_32x32x16_bf16 v[0:15], v[60:63], v[84:87], v[0:15]
	v_add_u32_e32 v40, v194, v205
	v_add_u32_e32 v42, v195, v205
	ds_read_b64_tr_b16 v[60:61], v40
	ds_read_b64_tr_b16 v[62:63], v42
	s_waitcnt lgkmcnt(12)
	v_mfma_f32_32x32x16_bf16 v[0:15], v[88:91], v[80:83], v[0:15]
	v_add_u32_e32 v40, v196, v205
	v_add_u32_e32 v42, v197, v205
	ds_read_b64_tr_b16 v[88:89], v40
	ds_read_b64_tr_b16 v[90:91], v42
	s_waitcnt lgkmcnt(12)
	v_mfma_f32_32x32x16_bf16 v[0:15], v[92:95], v[68:71], v[0:15]
	v_add_u32_e32 v40, v198, v205
	v_add_u32_e32 v42, v199, v205
	ds_read_b64_tr_b16 v[92:93], v40
	ds_read_b64_tr_b16 v[94:95], v42
	s_waitcnt lgkmcnt(12)
	v_mfma_f32_32x32x16_bf16 v[0:15], v[104:107], v[64:67], v[0:15]
	v_add_u32_e32 v40, v200, v205
	v_add_u32_e32 v42, v201, v205
	ds_read_b64_tr_b16 v[104:105], v40
	ds_read_b64_tr_b16 v[106:107], v42
	s_waitcnt lgkmcnt(12)
	v_mfma_f32_32x32x16_bf16 v[0:15], v[108:111], v[52:55], v[0:15]
	v_add_u32_e32 v40, v202, v205
	v_add_u32_e32 v42, v203, v205
	ds_read_b64_tr_b16 v[108:109], v40
	ds_read_b64_tr_b16 v[110:111], v42
	s_waitcnt lgkmcnt(12)
	v_mfma_f32_32x32x16_bf16 v[0:15], v[120:123], v[48:51], v[0:15]
	ds_read_b64_tr_b16 v[120:121], v186 offset:192
	ds_read_b64_tr_b16 v[122:123], v186 offset:4672
	s_waitcnt lgkmcnt(12)
	v_mfma_f32_32x32x16_bf16 v[0:15], v[56:59], v[36:39], v[0:15]
	ds_read_b64_tr_b16 v[56:57], v186 offset:9152
	ds_read_b64_tr_b16 v[58:59], v186 offset:13632
	s_waitcnt lgkmcnt(12)
	v_mfma_f32_32x32x16_bf16 v[0:15], v[60:63], v[32:35], v[0:15]
	ds_read_b64_tr_b16 v[60:61], v186 offset:18112
	ds_read_b64_tr_b16 v[62:63], v186 offset:22592
	s_waitcnt lgkmcnt(12)
	v_mfma_f32_32x32x16_bf16 v[0:15], v[88:91], v[20:23], v[0:15]
	ds_read_b64_tr_b16 v[88:89], v186 offset:27072
	ds_read_b64_tr_b16 v[90:91], v186 offset:31552
	s_waitcnt lgkmcnt(12)
	v_mfma_f32_32x32x16_bf16 v[0:15], v[92:95], v[16:19], v[0:15]
	ds_read_b64_tr_b16 v[92:93], v186 offset:36032
	ds_read_b64_tr_b16 v[94:95], v186 offset:40512
	s_waitcnt lgkmcnt(12)
	v_mfma_f32_32x32x16_bf16 v[0:15], v[104:107], v[28:31], v[0:15]
	ds_read_b64_tr_b16 v[104:105], v186 offset:44992
	ds_read_b64_tr_b16 v[106:107], v186 offset:49472
	s_waitcnt lgkmcnt(12)
	v_mfma_f32_32x32x16_bf16 v[0:15], v[108:111], v[24:27], v[0:15]
	ds_read_b64_tr_b16 v[108:109], v186 offset:53952
	ds_read_b64_tr_b16 v[110:111], v186 offset:58432
	s_nop 11
	v_pk_mul_f32 v[0:1], v[0:1], v[44:45] op_sel_hi:[1,0]
	v_pk_mul_f32 v[2:3], v[2:3], v[44:45] op_sel_hi:[1,0]
	v_pk_mul_f32 v[4:5], v[4:5], v[44:45] op_sel_hi:[1,0]
	v_pk_mul_f32 v[6:7], v[6:7], v[44:45] op_sel_hi:[1,0]
	v_cvt_pk_bf16_f32 v0, v0, v1
	v_cvt_pk_bf16_f32 v1, v2, v3
	v_cvt_pk_bf16_f32 v2, v4, v5
	v_cvt_pk_bf16_f32 v3, v6, v7
	s_nop 1
	v_permlane32_swap_b32_e32 v0, v2
	v_permlane32_swap_b32_e32 v1, v3
	global_store_dwordx4 v[124:125], v[0:3], off offset:128
	v_pk_mul_f32 v[8:9], v[8:9], v[44:45] op_sel_hi:[1,0]
	v_pk_mul_f32 v[10:11], v[10:11], v[44:45] op_sel_hi:[1,0]
	v_pk_mul_f32 v[12:13], v[12:13], v[44:45] op_sel_hi:[1,0]
	v_pk_mul_f32 v[14:15], v[14:15], v[44:45] op_sel_hi:[1,0]
	v_cvt_pk_bf16_f32 v4, v8, v9
	v_cvt_pk_bf16_f32 v5, v10, v11
	v_cvt_pk_bf16_f32 v6, v12, v13
	v_cvt_pk_bf16_f32 v7, v14, v15
	s_nop 1
	v_permlane32_swap_b32_e32 v4, v6
	v_permlane32_swap_b32_e32 v5, v7
	global_store_dwordx4 v[124:125], v[4:7], off offset:160
	s_nop 1
	s_waitcnt lgkmcnt(12)
	v_mfma_f32_32x32x16_bf16 v[0:15], v[120:123], v[116:119], 0
	v_add_u32_e32 v40, v187, v206
	ds_read_b64_tr_b16 v[120:121], v186 offset:62912
	ds_read_b64_tr_b16 v[122:123], v40
	s_waitcnt lgkmcnt(12)
	v_mfma_f32_32x32x16_bf16 v[0:15], v[56:59], v[112:115], v[0:15]
	v_add_u32_e32 v40, v188, v206
	v_add_u32_e32 v42, v189, v206
	ds_read_b64_tr_b16 v[56:57], v40
	ds_read_b64_tr_b16 v[58:59], v42
	s_waitcnt lgkmcnt(12)
	v_mfma_f32_32x32x16_bf16 v[0:15], v[60:63], v[100:103], v[0:15]
	v_add_u32_e32 v40, v190, v206
	v_add_u32_e32 v42, v191, v206
	ds_read_b64_tr_b16 v[60:61], v40
	ds_read_b64_tr_b16 v[62:63], v42
	s_waitcnt lgkmcnt(12)
	v_mfma_f32_32x32x16_bf16 v[0:15], v[88:91], v[96:99], v[0:15]
	v_add_u32_e32 v40, v192, v206
	v_add_u32_e32 v42, v193, v206
	ds_read_b64_tr_b16 v[88:89], v40
	ds_read_b64_tr_b16 v[90:91], v42
	s_waitcnt lgkmcnt(12)
	v_mfma_f32_32x32x16_bf16 v[0:15], v[92:95], v[84:87], v[0:15]
	v_add_u32_e32 v40, v194, v206
	v_add_u32_e32 v42, v195, v206
	ds_read_b64_tr_b16 v[92:93], v40
	ds_read_b64_tr_b16 v[94:95], v42
	s_waitcnt lgkmcnt(12)
	v_mfma_f32_32x32x16_bf16 v[0:15], v[104:107], v[80:83], v[0:15]
	v_add_u32_e32 v40, v196, v206
	v_add_u32_e32 v42, v197, v206
	ds_read_b64_tr_b16 v[104:105], v40
	ds_read_b64_tr_b16 v[106:107], v42
	s_waitcnt lgkmcnt(12)
	v_mfma_f32_32x32x16_bf16 v[0:15], v[108:111], v[68:71], v[0:15]
	v_add_u32_e32 v40, v198, v206
	v_add_u32_e32 v42, v199, v206
	ds_read_b64_tr_b16 v[108:109], v40
	ds_read_b64_tr_b16 v[110:111], v42
	s_waitcnt lgkmcnt(12)
	v_mfma_f32_32x32x16_bf16 v[0:15], v[120:123], v[64:67], v[0:15]
	v_add_u32_e32 v40, v200, v206
	v_add_u32_e32 v42, v201, v206
	ds_read_b64_tr_b16 v[120:121], v40
	ds_read_b64_tr_b16 v[122:123], v42
	s_waitcnt lgkmcnt(12)
	v_mfma_f32_32x32x16_bf16 v[0:15], v[56:59], v[52:55], v[0:15]
	v_add_u32_e32 v40, v202, v206
	v_add_u32_e32 v42, v203, v206
	ds_read_b64_tr_b16 v[56:57], v40
	ds_read_b64_tr_b16 v[58:59], v42
	s_waitcnt lgkmcnt(12)
	v_mfma_f32_32x32x16_bf16 v[0:15], v[60:63], v[48:51], v[0:15]
	ds_read_b64_tr_b16 v[60:61], v186 offset:256
	ds_read_b64_tr_b16 v[62:63], v186 offset:4736
	s_waitcnt lgkmcnt(12)
	v_mfma_f32_32x32x16_bf16 v[0:15], v[88:91], v[36:39], v[0:15]
	ds_read_b64_tr_b16 v[88:89], v186 offset:9216
	ds_read_b64_tr_b16 v[90:91], v186 offset:13696
	s_waitcnt lgkmcnt(12)
	v_mfma_f32_32x32x16_bf16 v[0:15], v[92:95], v[32:35], v[0:15]
	ds_read_b64_tr_b16 v[92:93], v186 offset:18176
	ds_read_b64_tr_b16 v[94:95], v186 offset:22656
	s_waitcnt lgkmcnt(12)
	v_mfma_f32_32x32x16_bf16 v[0:15], v[104:107], v[20:23], v[0:15]
	ds_read_b64_tr_b16 v[104:105], v186 offset:27136
	ds_read_b64_tr_b16 v[106:107], v186 offset:31616
	s_waitcnt lgkmcnt(12)
	v_mfma_f32_32x32x16_bf16 v[0:15], v[108:111], v[16:19], v[0:15]
	ds_read_b64_tr_b16 v[108:109], v186 offset:36096
	ds_read_b64_tr_b16 v[110:111], v186 offset:40576
	s_waitcnt lgkmcnt(12)
	v_mfma_f32_32x32x16_bf16 v[0:15], v[120:123], v[28:31], v[0:15]
	ds_read_b64_tr_b16 v[120:121], v186 offset:45056
	ds_read_b64_tr_b16 v[122:123], v186 offset:49536
	s_waitcnt lgkmcnt(12)
	v_mfma_f32_32x32x16_bf16 v[0:15], v[56:59], v[24:27], v[0:15]
	ds_read_b64_tr_b16 v[56:57], v186 offset:54016
	ds_read_b64_tr_b16 v[58:59], v186 offset:58496
	s_nop 11
	v_pk_mul_f32 v[0:1], v[0:1], v[44:45] op_sel_hi:[1,0]
	v_pk_mul_f32 v[2:3], v[2:3], v[44:45] op_sel_hi:[1,0]
	v_pk_mul_f32 v[4:5], v[4:5], v[44:45] op_sel_hi:[1,0]
	v_pk_mul_f32 v[6:7], v[6:7], v[44:45] op_sel_hi:[1,0]
	v_cvt_pk_bf16_f32 v0, v0, v1
	v_cvt_pk_bf16_f32 v1, v2, v3
	v_cvt_pk_bf16_f32 v2, v4, v5
	v_cvt_pk_bf16_f32 v3, v6, v7
	s_nop 1
	v_permlane32_swap_b32_e32 v0, v2
	v_permlane32_swap_b32_e32 v1, v3
	global_store_dwordx4 v[124:125], v[0:3], off offset:192
	v_pk_mul_f32 v[8:9], v[8:9], v[44:45] op_sel_hi:[1,0]
	v_pk_mul_f32 v[10:11], v[10:11], v[44:45] op_sel_hi:[1,0]
	v_pk_mul_f32 v[12:13], v[12:13], v[44:45] op_sel_hi:[1,0]
	v_pk_mul_f32 v[14:15], v[14:15], v[44:45] op_sel_hi:[1,0]
	v_cvt_pk_bf16_f32 v4, v8, v9
	v_cvt_pk_bf16_f32 v5, v10, v11
	v_cvt_pk_bf16_f32 v6, v12, v13
	v_cvt_pk_bf16_f32 v7, v14, v15
	s_nop 1
	v_permlane32_swap_b32_e32 v4, v6
	v_permlane32_swap_b32_e32 v5, v7
	global_store_dwordx4 v[124:125], v[4:7], off offset:224
	s_nop 1
	s_waitcnt lgkmcnt(12)
	v_mfma_f32_32x32x16_bf16 v[0:15], v[60:63], v[116:119], 0
	v_add_u32_e32 v40, v187, v207
	ds_read_b64_tr_b16 v[60:61], v186 offset:62976
	ds_read_b64_tr_b16 v[62:63], v40
	s_waitcnt lgkmcnt(12)
	v_mfma_f32_32x32x16_bf16 v[0:15], v[88:91], v[112:115], v[0:15]
	v_add_u32_e32 v40, v188, v207
	v_add_u32_e32 v42, v189, v207
	ds_read_b64_tr_b16 v[88:89], v40
	ds_read_b64_tr_b16 v[90:91], v42
	s_waitcnt lgkmcnt(12)
	v_mfma_f32_32x32x16_bf16 v[0:15], v[92:95], v[100:103], v[0:15]
	v_add_u32_e32 v40, v190, v207
	v_add_u32_e32 v42, v191, v207
	ds_read_b64_tr_b16 v[92:93], v40
	ds_read_b64_tr_b16 v[94:95], v42
	s_waitcnt lgkmcnt(12)
	v_mfma_f32_32x32x16_bf16 v[0:15], v[104:107], v[96:99], v[0:15]
	v_add_u32_e32 v40, v192, v207
	v_add_u32_e32 v42, v193, v207
	ds_read_b64_tr_b16 v[104:105], v40
	ds_read_b64_tr_b16 v[106:107], v42
	s_waitcnt lgkmcnt(12)
	v_mfma_f32_32x32x16_bf16 v[0:15], v[108:111], v[84:87], v[0:15]
	v_add_u32_e32 v40, v194, v207
	v_add_u32_e32 v42, v195, v207
	ds_read_b64_tr_b16 v[108:109], v40
	ds_read_b64_tr_b16 v[110:111], v42
	s_waitcnt lgkmcnt(12)
	v_mfma_f32_32x32x16_bf16 v[0:15], v[120:123], v[80:83], v[0:15]
	v_add_u32_e32 v40, v196, v207
	v_add_u32_e32 v42, v197, v207
	ds_read_b64_tr_b16 v[120:121], v40
	ds_read_b64_tr_b16 v[122:123], v42
	s_waitcnt lgkmcnt(12)
	v_mfma_f32_32x32x16_bf16 v[0:15], v[56:59], v[68:71], v[0:15]
	v_add_u32_e32 v40, v198, v207
	v_add_u32_e32 v42, v199, v207
	ds_read_b64_tr_b16 v[56:57], v40
	ds_read_b64_tr_b16 v[58:59], v42
	s_waitcnt lgkmcnt(12)
	v_mfma_f32_32x32x16_bf16 v[0:15], v[60:63], v[64:67], v[0:15]
	v_add_u32_e32 v40, v200, v207
	v_add_u32_e32 v42, v201, v207
	ds_read_b64_tr_b16 v[60:61], v40
	ds_read_b64_tr_b16 v[62:63], v42
	s_waitcnt lgkmcnt(12)
	v_mfma_f32_32x32x16_bf16 v[0:15], v[88:91], v[52:55], v[0:15]
	v_add_u32_e32 v40, v202, v207
	v_add_u32_e32 v42, v203, v207
	ds_read_b64_tr_b16 v[88:89], v40
	ds_read_b64_tr_b16 v[90:91], v42
	s_waitcnt lgkmcnt(12)
	v_mfma_f32_32x32x16_bf16 v[0:15], v[92:95], v[48:51], v[0:15]
	ds_read_b64_tr_b16 v[92:93], v186 offset:320
	ds_read_b64_tr_b16 v[94:95], v186 offset:4800
	s_waitcnt lgkmcnt(12)
	v_mfma_f32_32x32x16_bf16 v[0:15], v[104:107], v[36:39], v[0:15]
	ds_read_b64_tr_b16 v[104:105], v186 offset:9280
	ds_read_b64_tr_b16 v[106:107], v186 offset:13760
	s_waitcnt lgkmcnt(12)
	v_mfma_f32_32x32x16_bf16 v[0:15], v[108:111], v[32:35], v[0:15]
	ds_read_b64_tr_b16 v[108:109], v186 offset:18240
	ds_read_b64_tr_b16 v[110:111], v186 offset:22720
	s_waitcnt lgkmcnt(12)
	v_mfma_f32_32x32x16_bf16 v[0:15], v[120:123], v[20:23], v[0:15]
	ds_read_b64_tr_b16 v[120:121], v186 offset:27200
	ds_read_b64_tr_b16 v[122:123], v186 offset:31680
	s_waitcnt lgkmcnt(12)
	v_mfma_f32_32x32x16_bf16 v[0:15], v[56:59], v[16:19], v[0:15]
	ds_read_b64_tr_b16 v[56:57], v186 offset:36160
	ds_read_b64_tr_b16 v[58:59], v186 offset:40640
	s_waitcnt lgkmcnt(12)
	v_mfma_f32_32x32x16_bf16 v[0:15], v[60:63], v[28:31], v[0:15]
	ds_read_b64_tr_b16 v[60:61], v186 offset:45120
	ds_read_b64_tr_b16 v[62:63], v186 offset:49600
	s_waitcnt lgkmcnt(12)
	v_mfma_f32_32x32x16_bf16 v[0:15], v[88:91], v[24:27], v[0:15]
	ds_read_b64_tr_b16 v[88:89], v186 offset:54080
	ds_read_b64_tr_b16 v[90:91], v186 offset:58560
	s_nop 11
	v_pk_mul_f32 v[0:1], v[0:1], v[44:45] op_sel_hi:[1,0]
	v_pk_mul_f32 v[2:3], v[2:3], v[44:45] op_sel_hi:[1,0]
	v_pk_mul_f32 v[4:5], v[4:5], v[44:45] op_sel_hi:[1,0]
	v_pk_mul_f32 v[6:7], v[6:7], v[44:45] op_sel_hi:[1,0]
	v_cvt_pk_bf16_f32 v0, v0, v1
	v_cvt_pk_bf16_f32 v1, v2, v3
	v_cvt_pk_bf16_f32 v2, v4, v5
	v_cvt_pk_bf16_f32 v3, v6, v7
	s_nop 1
	v_permlane32_swap_b32_e32 v0, v2
	v_permlane32_swap_b32_e32 v1, v3
	global_store_dwordx4 v[124:125], v[0:3], off offset:256
	v_pk_mul_f32 v[8:9], v[8:9], v[44:45] op_sel_hi:[1,0]
	v_pk_mul_f32 v[10:11], v[10:11], v[44:45] op_sel_hi:[1,0]
	v_pk_mul_f32 v[12:13], v[12:13], v[44:45] op_sel_hi:[1,0]
	v_pk_mul_f32 v[14:15], v[14:15], v[44:45] op_sel_hi:[1,0]
	v_cvt_pk_bf16_f32 v4, v8, v9
	v_cvt_pk_bf16_f32 v5, v10, v11
	v_cvt_pk_bf16_f32 v6, v12, v13
	v_cvt_pk_bf16_f32 v7, v14, v15
	s_nop 1
	v_permlane32_swap_b32_e32 v4, v6
	v_permlane32_swap_b32_e32 v5, v7
	global_store_dwordx4 v[124:125], v[4:7], off offset:288
	s_nop 1
	s_waitcnt lgkmcnt(12)
	v_mfma_f32_32x32x16_bf16 v[0:15], v[92:95], v[116:119], 0
	v_add_u32_e32 v40, v187, v208
	ds_read_b64_tr_b16 v[92:93], v186 offset:63040
	ds_read_b64_tr_b16 v[94:95], v40
	s_waitcnt lgkmcnt(12)
	v_mfma_f32_32x32x16_bf16 v[0:15], v[104:107], v[112:115], v[0:15]
	v_add_u32_e32 v40, v188, v208
	v_add_u32_e32 v42, v189, v208
	ds_read_b64_tr_b16 v[104:105], v40
	ds_read_b64_tr_b16 v[106:107], v42
	s_waitcnt lgkmcnt(12)
	v_mfma_f32_32x32x16_bf16 v[0:15], v[108:111], v[100:103], v[0:15]
	v_add_u32_e32 v40, v190, v208
	v_add_u32_e32 v42, v191, v208
	ds_read_b64_tr_b16 v[108:109], v40
	ds_read_b64_tr_b16 v[110:111], v42
	s_waitcnt lgkmcnt(12)
	v_mfma_f32_32x32x16_bf16 v[0:15], v[120:123], v[96:99], v[0:15]
	v_add_u32_e32 v40, v192, v208
	v_add_u32_e32 v42, v193, v208
	ds_read_b64_tr_b16 v[120:121], v40
	ds_read_b64_tr_b16 v[122:123], v42
	s_waitcnt lgkmcnt(12)
	v_mfma_f32_32x32x16_bf16 v[0:15], v[56:59], v[84:87], v[0:15]
	v_add_u32_e32 v40, v194, v208
	v_add_u32_e32 v42, v195, v208
	ds_read_b64_tr_b16 v[56:57], v40
	ds_read_b64_tr_b16 v[58:59], v42
	s_waitcnt lgkmcnt(12)
	v_mfma_f32_32x32x16_bf16 v[0:15], v[60:63], v[80:83], v[0:15]
	v_add_u32_e32 v40, v196, v208
	v_add_u32_e32 v42, v197, v208
	ds_read_b64_tr_b16 v[60:61], v40
	ds_read_b64_tr_b16 v[62:63], v42
	s_waitcnt lgkmcnt(12)
	v_mfma_f32_32x32x16_bf16 v[0:15], v[88:91], v[68:71], v[0:15]
	v_add_u32_e32 v40, v198, v208
	v_add_u32_e32 v42, v199, v208
	ds_read_b64_tr_b16 v[88:89], v40
	ds_read_b64_tr_b16 v[90:91], v42
	s_waitcnt lgkmcnt(12)
	v_mfma_f32_32x32x16_bf16 v[0:15], v[92:95], v[64:67], v[0:15]
	v_add_u32_e32 v40, v200, v208
	v_add_u32_e32 v42, v201, v208
	ds_read_b64_tr_b16 v[92:93], v40
	ds_read_b64_tr_b16 v[94:95], v42
	s_waitcnt lgkmcnt(12)
	v_mfma_f32_32x32x16_bf16 v[0:15], v[104:107], v[52:55], v[0:15]
	v_add_u32_e32 v40, v202, v208
	v_add_u32_e32 v42, v203, v208
	ds_read_b64_tr_b16 v[104:105], v40
	ds_read_b64_tr_b16 v[106:107], v42
	s_waitcnt lgkmcnt(12)
	v_mfma_f32_32x32x16_bf16 v[0:15], v[108:111], v[48:51], v[0:15]
	ds_read_b64_tr_b16 v[108:109], v186 offset:384
	ds_read_b64_tr_b16 v[110:111], v186 offset:4864
	s_waitcnt lgkmcnt(12)
	v_mfma_f32_32x32x16_bf16 v[0:15], v[120:123], v[36:39], v[0:15]
	ds_read_b64_tr_b16 v[120:121], v186 offset:9344
	ds_read_b64_tr_b16 v[122:123], v186 offset:13824
	s_waitcnt lgkmcnt(12)
	v_mfma_f32_32x32x16_bf16 v[0:15], v[56:59], v[32:35], v[0:15]
	ds_read_b64_tr_b16 v[56:57], v186 offset:18304
	ds_read_b64_tr_b16 v[58:59], v186 offset:22784
	s_waitcnt lgkmcnt(12)
	v_mfma_f32_32x32x16_bf16 v[0:15], v[60:63], v[20:23], v[0:15]
	ds_read_b64_tr_b16 v[60:61], v186 offset:27264
	ds_read_b64_tr_b16 v[62:63], v186 offset:31744
	s_waitcnt lgkmcnt(12)
	v_mfma_f32_32x32x16_bf16 v[0:15], v[88:91], v[16:19], v[0:15]
	ds_read_b64_tr_b16 v[88:89], v186 offset:36224
	ds_read_b64_tr_b16 v[90:91], v186 offset:40704
	s_waitcnt lgkmcnt(12)
	v_mfma_f32_32x32x16_bf16 v[0:15], v[92:95], v[28:31], v[0:15]
	ds_read_b64_tr_b16 v[92:93], v186 offset:45184
	ds_read_b64_tr_b16 v[94:95], v186 offset:49664
	s_waitcnt lgkmcnt(12)
	v_mfma_f32_32x32x16_bf16 v[0:15], v[104:107], v[24:27], v[0:15]
	ds_read_b64_tr_b16 v[104:105], v186 offset:54144
	ds_read_b64_tr_b16 v[106:107], v186 offset:58624
	s_nop 11
	v_pk_mul_f32 v[0:1], v[0:1], v[44:45] op_sel_hi:[1,0]
	v_pk_mul_f32 v[2:3], v[2:3], v[44:45] op_sel_hi:[1,0]
	v_pk_mul_f32 v[4:5], v[4:5], v[44:45] op_sel_hi:[1,0]
	v_pk_mul_f32 v[6:7], v[6:7], v[44:45] op_sel_hi:[1,0]
	v_cvt_pk_bf16_f32 v0, v0, v1
	v_cvt_pk_bf16_f32 v1, v2, v3
	v_cvt_pk_bf16_f32 v2, v4, v5
	v_cvt_pk_bf16_f32 v3, v6, v7
	s_nop 1
	v_permlane32_swap_b32_e32 v0, v2
	v_permlane32_swap_b32_e32 v1, v3
	global_store_dwordx4 v[124:125], v[0:3], off offset:320
	v_pk_mul_f32 v[8:9], v[8:9], v[44:45] op_sel_hi:[1,0]
	v_pk_mul_f32 v[10:11], v[10:11], v[44:45] op_sel_hi:[1,0]
	v_pk_mul_f32 v[12:13], v[12:13], v[44:45] op_sel_hi:[1,0]
	v_pk_mul_f32 v[14:15], v[14:15], v[44:45] op_sel_hi:[1,0]
	v_cvt_pk_bf16_f32 v4, v8, v9
	v_cvt_pk_bf16_f32 v5, v10, v11
	v_cvt_pk_bf16_f32 v6, v12, v13
	v_cvt_pk_bf16_f32 v7, v14, v15
	s_nop 1
	v_permlane32_swap_b32_e32 v4, v6
	v_permlane32_swap_b32_e32 v5, v7
	global_store_dwordx4 v[124:125], v[4:7], off offset:352
	s_nop 1
	s_waitcnt lgkmcnt(12)
	v_mfma_f32_32x32x16_bf16 v[0:15], v[108:111], v[116:119], 0
	v_add_u32_e32 v40, v187, v209
	ds_read_b64_tr_b16 v[108:109], v186 offset:63104
	ds_read_b64_tr_b16 v[110:111], v40
	s_waitcnt lgkmcnt(12)
	v_mfma_f32_32x32x16_bf16 v[0:15], v[120:123], v[112:115], v[0:15]
	v_add_u32_e32 v40, v188, v209
	v_add_u32_e32 v42, v189, v209
	ds_read_b64_tr_b16 v[120:121], v40
	ds_read_b64_tr_b16 v[122:123], v42
	s_waitcnt lgkmcnt(12)
	v_mfma_f32_32x32x16_bf16 v[0:15], v[56:59], v[100:103], v[0:15]
	v_add_u32_e32 v40, v190, v209
	v_add_u32_e32 v42, v191, v209
	ds_read_b64_tr_b16 v[56:57], v40
	ds_read_b64_tr_b16 v[58:59], v42
	s_waitcnt lgkmcnt(12)
	v_mfma_f32_32x32x16_bf16 v[0:15], v[60:63], v[96:99], v[0:15]
	v_add_u32_e32 v40, v192, v209
	v_add_u32_e32 v42, v193, v209
	ds_read_b64_tr_b16 v[60:61], v40
	ds_read_b64_tr_b16 v[62:63], v42
	s_waitcnt lgkmcnt(12)
	v_mfma_f32_32x32x16_bf16 v[0:15], v[88:91], v[84:87], v[0:15]
	v_add_u32_e32 v40, v194, v209
	v_add_u32_e32 v42, v195, v209
	ds_read_b64_tr_b16 v[88:89], v40
	ds_read_b64_tr_b16 v[90:91], v42
	s_waitcnt lgkmcnt(12)
	v_mfma_f32_32x32x16_bf16 v[0:15], v[92:95], v[80:83], v[0:15]
	v_add_u32_e32 v40, v196, v209
	v_add_u32_e32 v42, v197, v209
	ds_read_b64_tr_b16 v[92:93], v40
	ds_read_b64_tr_b16 v[94:95], v42
	s_waitcnt lgkmcnt(12)
	v_mfma_f32_32x32x16_bf16 v[0:15], v[104:107], v[68:71], v[0:15]
	v_add_u32_e32 v40, v198, v209
	v_add_u32_e32 v42, v199, v209
	ds_read_b64_tr_b16 v[104:105], v40
	ds_read_b64_tr_b16 v[106:107], v42
	s_waitcnt lgkmcnt(12)
	v_mfma_f32_32x32x16_bf16 v[0:15], v[108:111], v[64:67], v[0:15]
	v_add_u32_e32 v40, v200, v209
	v_add_u32_e32 v42, v201, v209
	ds_read_b64_tr_b16 v[108:109], v40
	ds_read_b64_tr_b16 v[110:111], v42
	s_waitcnt lgkmcnt(12)
	v_mfma_f32_32x32x16_bf16 v[0:15], v[120:123], v[52:55], v[0:15]
	v_add_u32_e32 v40, v202, v209
	v_add_u32_e32 v42, v203, v209
	ds_read_b64_tr_b16 v[120:121], v40
	ds_read_b64_tr_b16 v[122:123], v42
	s_waitcnt lgkmcnt(12)
	v_mfma_f32_32x32x16_bf16 v[0:15], v[56:59], v[48:51], v[0:15]
	ds_read_b64_tr_b16 v[56:57], v186 offset:448
	ds_read_b64_tr_b16 v[58:59], v186 offset:4928
	s_waitcnt lgkmcnt(12)
	v_mfma_f32_32x32x16_bf16 v[0:15], v[60:63], v[36:39], v[0:15]
	ds_read_b64_tr_b16 v[60:61], v186 offset:9408
	ds_read_b64_tr_b16 v[62:63], v186 offset:13888
	s_waitcnt lgkmcnt(12)
	v_mfma_f32_32x32x16_bf16 v[0:15], v[88:91], v[32:35], v[0:15]
	ds_read_b64_tr_b16 v[88:89], v186 offset:18368
	ds_read_b64_tr_b16 v[90:91], v186 offset:22848
	s_waitcnt lgkmcnt(12)
	v_mfma_f32_32x32x16_bf16 v[0:15], v[92:95], v[20:23], v[0:15]
	ds_read_b64_tr_b16 v[92:93], v186 offset:27328
	ds_read_b64_tr_b16 v[94:95], v186 offset:31808
	s_waitcnt lgkmcnt(12)
	v_mfma_f32_32x32x16_bf16 v[0:15], v[104:107], v[16:19], v[0:15]
	ds_read_b64_tr_b16 v[104:105], v186 offset:36288
	ds_read_b64_tr_b16 v[106:107], v186 offset:40768
	s_waitcnt lgkmcnt(12)
	v_mfma_f32_32x32x16_bf16 v[0:15], v[108:111], v[28:31], v[0:15]
	ds_read_b64_tr_b16 v[108:109], v186 offset:45248
	ds_read_b64_tr_b16 v[110:111], v186 offset:49728
	s_waitcnt lgkmcnt(12)
	v_mfma_f32_32x32x16_bf16 v[0:15], v[120:123], v[24:27], v[0:15]
	ds_read_b64_tr_b16 v[120:121], v186 offset:54208
	ds_read_b64_tr_b16 v[122:123], v186 offset:58688
	s_nop 11
	v_pk_mul_f32 v[0:1], v[0:1], v[44:45] op_sel_hi:[1,0]
	v_pk_mul_f32 v[2:3], v[2:3], v[44:45] op_sel_hi:[1,0]
	v_pk_mul_f32 v[4:5], v[4:5], v[44:45] op_sel_hi:[1,0]
	v_pk_mul_f32 v[6:7], v[6:7], v[44:45] op_sel_hi:[1,0]
	v_cvt_pk_bf16_f32 v0, v0, v1
	v_cvt_pk_bf16_f32 v1, v2, v3
	v_cvt_pk_bf16_f32 v2, v4, v5
	v_cvt_pk_bf16_f32 v3, v6, v7
	s_nop 1
	v_permlane32_swap_b32_e32 v0, v2
	v_permlane32_swap_b32_e32 v1, v3
	global_store_dwordx4 v[124:125], v[0:3], off offset:384
	v_pk_mul_f32 v[8:9], v[8:9], v[44:45] op_sel_hi:[1,0]
	v_pk_mul_f32 v[10:11], v[10:11], v[44:45] op_sel_hi:[1,0]
	v_pk_mul_f32 v[12:13], v[12:13], v[44:45] op_sel_hi:[1,0]
	v_pk_mul_f32 v[14:15], v[14:15], v[44:45] op_sel_hi:[1,0]
	v_cvt_pk_bf16_f32 v4, v8, v9
	v_cvt_pk_bf16_f32 v5, v10, v11
	v_cvt_pk_bf16_f32 v6, v12, v13
	v_cvt_pk_bf16_f32 v7, v14, v15
	s_nop 1
	v_permlane32_swap_b32_e32 v4, v6
	v_permlane32_swap_b32_e32 v5, v7
	global_store_dwordx4 v[124:125], v[4:7], off offset:416
	s_nop 1
	s_waitcnt lgkmcnt(12)
	v_mfma_f32_32x32x16_bf16 v[0:15], v[56:59], v[116:119], 0
	v_add_u32_e32 v40, v187, v210
	ds_read_b64_tr_b16 v[56:57], v186 offset:63168
	ds_read_b64_tr_b16 v[58:59], v40
	s_waitcnt lgkmcnt(12)
	v_mfma_f32_32x32x16_bf16 v[0:15], v[60:63], v[112:115], v[0:15]
	v_add_u32_e32 v40, v188, v210
	v_add_u32_e32 v42, v189, v210
	ds_read_b64_tr_b16 v[60:61], v40
	ds_read_b64_tr_b16 v[62:63], v42
	s_waitcnt lgkmcnt(12)
	v_mfma_f32_32x32x16_bf16 v[0:15], v[88:91], v[100:103], v[0:15]
	v_add_u32_e32 v40, v190, v210
	v_add_u32_e32 v42, v191, v210
	ds_read_b64_tr_b16 v[88:89], v40
	ds_read_b64_tr_b16 v[90:91], v42
	s_waitcnt lgkmcnt(12)
	v_mfma_f32_32x32x16_bf16 v[0:15], v[92:95], v[96:99], v[0:15]
	v_add_u32_e32 v40, v192, v210
	v_add_u32_e32 v42, v193, v210
	ds_read_b64_tr_b16 v[92:93], v40
	ds_read_b64_tr_b16 v[94:95], v42
	s_waitcnt lgkmcnt(12)
	v_mfma_f32_32x32x16_bf16 v[0:15], v[104:107], v[84:87], v[0:15]
	v_add_u32_e32 v40, v194, v210
	v_add_u32_e32 v42, v195, v210
	ds_read_b64_tr_b16 v[104:105], v40
	ds_read_b64_tr_b16 v[106:107], v42
	s_waitcnt lgkmcnt(12)
	v_mfma_f32_32x32x16_bf16 v[0:15], v[108:111], v[80:83], v[0:15]
	v_add_u32_e32 v40, v196, v210
	v_add_u32_e32 v42, v197, v210
	ds_read_b64_tr_b16 v[108:109], v40
	ds_read_b64_tr_b16 v[110:111], v42
	s_waitcnt lgkmcnt(12)
	v_mfma_f32_32x32x16_bf16 v[0:15], v[120:123], v[68:71], v[0:15]
	v_add_u32_e32 v40, v198, v210
	v_add_u32_e32 v42, v199, v210
	ds_read_b64_tr_b16 v[120:121], v40
	ds_read_b64_tr_b16 v[122:123], v42
	s_waitcnt lgkmcnt(12)
	v_mfma_f32_32x32x16_bf16 v[0:15], v[56:59], v[64:67], v[0:15]
	v_add_u32_e32 v40, v200, v210
	v_add_u32_e32 v42, v201, v210
	ds_read_b64_tr_b16 v[56:57], v40
	ds_read_b64_tr_b16 v[58:59], v42
	s_waitcnt lgkmcnt(12)
	v_mfma_f32_32x32x16_bf16 v[0:15], v[60:63], v[52:55], v[0:15]
	v_add_u32_e32 v40, v202, v210
	v_add_u32_e32 v42, v203, v210
	ds_read_b64_tr_b16 v[60:61], v40
	ds_read_b64_tr_b16 v[62:63], v42
	s_waitcnt lgkmcnt(12)
	v_mfma_f32_32x32x16_bf16 v[0:15], v[88:91], v[48:51], v[0:15]
	s_waitcnt lgkmcnt(10)
	v_mfma_f32_32x32x16_bf16 v[0:15], v[92:95], v[36:39], v[0:15]
	s_waitcnt lgkmcnt(8)
	v_mfma_f32_32x32x16_bf16 v[0:15], v[104:107], v[32:35], v[0:15]
	s_waitcnt lgkmcnt(6)
	v_mfma_f32_32x32x16_bf16 v[0:15], v[108:111], v[20:23], v[0:15]
	s_waitcnt lgkmcnt(4)
	v_mfma_f32_32x32x16_bf16 v[0:15], v[120:123], v[16:19], v[0:15]
	s_waitcnt lgkmcnt(2)
	v_mfma_f32_32x32x16_bf16 v[0:15], v[56:59], v[28:31], v[0:15]
	s_waitcnt lgkmcnt(0)
	v_mfma_f32_32x32x16_bf16 v[0:15], v[60:63], v[24:27], v[0:15]
	s_nop 11
	v_pk_mul_f32 v[0:1], v[0:1], v[44:45] op_sel_hi:[1,0]
	v_pk_mul_f32 v[2:3], v[2:3], v[44:45] op_sel_hi:[1,0]
	v_pk_mul_f32 v[4:5], v[4:5], v[44:45] op_sel_hi:[1,0]
	v_pk_mul_f32 v[6:7], v[6:7], v[44:45] op_sel_hi:[1,0]
	v_cvt_pk_bf16_f32 v0, v0, v1
	v_cvt_pk_bf16_f32 v1, v2, v3
	v_cvt_pk_bf16_f32 v2, v4, v5
	v_cvt_pk_bf16_f32 v3, v6, v7
	s_nop 1
	v_permlane32_swap_b32_e32 v0, v2
	v_permlane32_swap_b32_e32 v1, v3
	global_store_dwordx4 v[124:125], v[0:3], off offset:448
	v_pk_mul_f32 v[8:9], v[8:9], v[44:45] op_sel_hi:[1,0]
	v_pk_mul_f32 v[10:11], v[10:11], v[44:45] op_sel_hi:[1,0]
	v_pk_mul_f32 v[12:13], v[12:13], v[44:45] op_sel_hi:[1,0]
	v_pk_mul_f32 v[14:15], v[14:15], v[44:45] op_sel_hi:[1,0]
	v_cvt_pk_bf16_f32 v4, v8, v9
	v_cvt_pk_bf16_f32 v5, v10, v11
	v_cvt_pk_bf16_f32 v6, v12, v13
	v_cvt_pk_bf16_f32 v7, v14, v15
	s_nop 1
	v_permlane32_swap_b32_e32 v4, v6
	v_permlane32_swap_b32_e32 v5, v7
	global_store_dwordx4 v[124:125], v[4:7], off offset:480
	s_nop 1
	s_barrier
	s_branch .LBB0_751
